# GEMM K-loops: back edge rotated in front of the loop-back barrier (strategy 7.11, barrier becomes the loop head, exit path gets its own copy)
# baseline (speedup 1.0000x reference)
; #define PG8_STAGE(bufoff, gbase, voff) do { _Pragma("unroll") for (int _i = 0; _i < 2; ++_i) \
;         __builtin_amdgcn_global_load_lds((const unsigned*)((const char*)(gbase) + (voff)[_i]), (LAS unsigned*)(lds + (bufoff) + ldsw + _i * 8192), 16, 0, 0); } while (0)
; #define PG8_LDA(dst, b, h) do { _Pragma("unroll") for (int m = 0; m < 4; ++m) _Pragma("unroll") for (int k = 0; k < 2; ++k) dst[m][k] = *(const LAS bf16x8*)(lds + PG8_SA(b, h) + aoff + m * 2048 + k * 1024); } while (0)
; #define PG8_LDB(dst, b, h) do { _Pragma("unroll") for (int n = 0; n < 2; ++n) _Pragma("unroll") for (int k = 0; k < 2; ++k) dst[n][k] = *(const LAS bf16x8*)(lds + PG8_SB(b, h) + boff + n * 2048 + k * 1024); } while (0)
; #define PG8_MMA(ai, bj, At, Bt) do { __builtin_amdgcn_s_setprio(1); _Pragma("unroll") for (int m = 0; m < 4; ++m) _Pragma("unroll") for (int n = 0; n < 2; ++n) _Pragma("unroll") for (int k = 0; k < 2; ++k) \
;         acc[ai][bj][m][n] = __builtin_amdgcn_mfma_f32_16x16x32_bf16(Bt[n][k], At[m][k], acc[ai][bj][m][n], 0, 0, 0); __builtin_amdgcn_s_setprio(0); } while (0)
; #define PG8_WAIT_L(n) asm volatile("s_waitcnt lgkmcnt(" #n ")" ::: "memory")
; #define PG8_BAR __builtin_amdgcn_s_barrier()
; #define PG8_SCHED __builtin_amdgcn_sched_barrier(0)
; template <class Epi>
; __device__ __forceinline__ void gemm_phase(LAS unsigned char* lds, const Gemm g, const StaticOrder& S, const Epi& E, int wv) {
;     ...
;         for (int t = 0; t < nt; t += 2) {
;             const bool last = (t == nt - 2);
;             const char* a1 = cA + (size_t)(t + 1) * kstep;
;             const char* a2 = last ? nA : cA + (size_t)(t + 2) * kstep; const char* b2 = last ? nB : cB + (size_t)(t + 2) * kstep;
;             const char* a3 = a2 + kstep; const char* b3 = b2 + kstep;
;             PG8_LDB(B0, 0, 0); PG8_SCHED; PG8_LDA(At, 0, 0); PG8_STAGE(PG8_SA(1, 1), a1 + hstep, voffA);
;             PG8_WAIT_L(8); PG8_BAR; PG8_WAIT_L(0); PG8_MMA(0, 0, At, B0); PG8_BAR; PG8_SCHED;
;             PG8_LDB(B1, 0, 1); PG8_STAGE(PG8_SB(0, 0), b2, voffB);
;             PG8_BAR; PG8_WAIT_L(0); PG8_MMA(0, 1, At, B1); PG8_BAR;
;             PG8_LDA(At, 0, 1); PG8_STAGE(PG8_SA(0, 0), a2, voffA);
;             PG8_BAR; PG8_WAIT_L(0); PG8_MMA(1, 0, At, B0); PG8_BAR; PG8_SCHED;
.LBB0_215:
	s_barrier
	ds_read_b128 v[146:149], v153
	ds_read_b128 v[156:159], v153 offset:1024
	ds_read_b128 v[160:163], v153 offset:2048
	ds_read_b128 v[164:167], v153 offset:3072
	s_add_u32 s42, s40, 0x100
	s_addc_u32 s43, s41, 0
	s_cmp_eq_u32 s70, 12
	s_cselect_b32 s47, s7, s43
	s_cselect_b32 s46, s9, s42
	s_cselect_b32 s45, s31, s69
	s_cselect_b32 s44, s35, s68
	ds_read_b128 v[168:171], v154
	ds_read_b128 v[172:175], v154 offset:1024
	ds_read_b128 v[176:179], v154 offset:2048
	ds_read_b128 v[180:183], v154 offset:3072
	ds_read_b128 v[184:187], v154 offset:4096
	ds_read_b128 v[188:191], v154 offset:5120
	ds_read_b128 v[192:195], v154 offset:6144
	ds_read_b128 v[196:199], v154 offset:7168
	ds_read_b128 v[200:203], v155
	ds_read_b128 v[204:207], v155 offset:1024
	ds_read_b128 v[208:211], v155 offset:2048
	ds_read_b128 v[212:215], v155 offset:3072
	v_lshl_add_u64 v[252:253], s[40:41], 0, v[138:139]
	s_add_i32 m0, s50, 0xc000
	s_nop 0
	global_load_lds_dwordx4 v[252:253], off
	v_lshl_add_u64 v[252:253], s[40:41], 0, v[140:141]
	s_add_i32 m0, s50, 0xe000
	s_nop 0
	global_load_lds_dwordx4 v[252:253], off
	s_waitcnt vmcnt(8)
	s_waitcnt lgkmcnt(0)
	s_barrier
	s_setprio 1
	v_mfma_f32_16x16x32_bf16 v[124:127], v[146:149], v[168:171], v[124:127]
	v_mfma_f32_16x16x32_bf16 v[120:123], v[160:163], v[168:171], v[120:123]
	v_mfma_f32_16x16x32_bf16 v[108:111], v[146:149], v[176:179], v[108:111]
	v_mfma_f32_16x16x32_bf16 v[104:107], v[160:163], v[176:179], v[104:107]
	v_mfma_f32_16x16x32_bf16 v[92:95], v[146:149], v[184:187], v[92:95]
	v_mfma_f32_16x16x32_bf16 v[88:91], v[160:163], v[184:187], v[88:91]
	v_mfma_f32_16x16x32_bf16 v[76:79], v[146:149], v[192:195], v[76:79]
	v_mfma_f32_16x16x32_bf16 v[72:75], v[160:163], v[192:195], v[72:75]
	v_mfma_f32_16x16x32_bf16 v[124:127], v[156:159], v[172:175], v[124:127]
	v_mfma_f32_16x16x32_bf16 v[120:123], v[164:167], v[172:175], v[120:123]
	v_mfma_f32_16x16x32_bf16 v[108:111], v[156:159], v[180:183], v[108:111]
	v_mfma_f32_16x16x32_bf16 v[104:107], v[164:167], v[180:183], v[104:107]
	v_mfma_f32_16x16x32_bf16 v[92:95], v[156:159], v[188:191], v[92:95]
	v_mfma_f32_16x16x32_bf16 v[88:91], v[164:167], v[188:191], v[88:91]
	v_mfma_f32_16x16x32_bf16 v[76:79], v[156:159], v[196:199], v[76:79]
	v_mfma_f32_16x16x32_bf16 v[72:75], v[164:167], v[196:199], v[72:75]
	v_mfma_f32_16x16x32_bf16 v[116:119], v[200:203], v[168:171], v[116:119]
	v_mfma_f32_16x16x32_bf16 v[112:115], v[208:211], v[168:171], v[112:115]
	v_mfma_f32_16x16x32_bf16 v[100:103], v[200:203], v[176:179], v[100:103]
	v_mfma_f32_16x16x32_bf16 v[96:99], v[208:211], v[176:179], v[96:99]
	v_mfma_f32_16x16x32_bf16 v[84:87], v[200:203], v[184:187], v[84:87]
	v_mfma_f32_16x16x32_bf16 v[80:83], v[208:211], v[184:187], v[80:83]
	v_mfma_f32_16x16x32_bf16 v[68:71], v[200:203], v[192:195], v[68:71]
	v_mfma_f32_16x16x32_bf16 v[64:67], v[208:211], v[192:195], v[64:67]
	v_mfma_f32_16x16x32_bf16 v[116:119], v[204:207], v[172:175], v[116:119]
	v_mfma_f32_16x16x32_bf16 v[112:115], v[212:215], v[172:175], v[112:115]
	v_mfma_f32_16x16x32_bf16 v[100:103], v[204:207], v[180:183], v[100:103]
	v_mfma_f32_16x16x32_bf16 v[96:99], v[212:215], v[180:183], v[96:99]
	v_mfma_f32_16x16x32_bf16 v[84:87], v[204:207], v[188:191], v[84:87]
	v_mfma_f32_16x16x32_bf16 v[80:83], v[212:215], v[188:191], v[80:83]
	v_mfma_f32_16x16x32_bf16 v[68:71], v[204:207], v[196:199], v[68:71]
	v_mfma_f32_16x16x32_bf16 v[64:67], v[212:215], v[196:199], v[64:67]
	s_setprio 0
	s_barrier
	ds_read_b128 v[168:171], v154 offset:16384
	ds_read_b128 v[172:175], v154 offset:17408
	ds_read_b128 v[176:179], v154 offset:18432
	ds_read_b128 v[180:183], v154 offset:19456
	ds_read_b128 v[184:187], v154 offset:20480
	ds_read_b128 v[188:191], v154 offset:21504
	ds_read_b128 v[192:195], v154 offset:22528
	ds_read_b128 v[196:199], v154 offset:23552
	s_add_i32 s40, s65, s49
	v_lshl_add_u64 v[150:151], s[44:45], 0, v[130:131]
	s_mov_b32 m0, s40
	s_nop 0
	global_load_lds_dwordx4 v[150:151], off
	v_lshl_add_u64 v[216:217], s[44:45], 0, v[134:135]
	s_add_i32 m0, s40, 0x2000
	s_nop 0
	global_load_lds_dwordx4 v[216:217], off
	s_mov_b32 m0, s50
	v_lshl_add_u64 v[218:219], s[46:47], 0, v[128:129]
	global_load_lds_dwordx4 v[218:219], off
	v_lshl_add_u64 v[220:221], s[46:47], 0, v[132:133]
	s_mov_b32 m0, s51
	s_nop 0
	global_load_lds_dwordx4 v[220:221], off
	s_add_u32 s40, s44, 0x40000
	s_addc_u32 s41, s45, 0
	s_add_i32 s71, s66, s49
	v_lshl_add_u64 v[254:255], s[40:41], 0, v[130:131]
	s_mov_b32 m0, s71
	s_nop 0
	global_load_lds_dwordx4 v[254:255], off
	v_lshl_add_u64 v[254:255], s[40:41], 0, v[134:135]
	s_add_i32 m0, s71, 0x2000
	s_nop 0
	global_load_lds_dwordx4 v[254:255], off
	s_waitcnt vmcnt(8)
	s_waitcnt lgkmcnt(0)
	s_barrier
; #define PG8_STAGE(bufoff, gbase, voff) do { _Pragma("unroll") for (int _i = 0; _i < 2; ++_i) \
;         __builtin_amdgcn_global_load_lds((const unsigned*)((const char*)(gbase) + (voff)[_i]), (LAS unsigned*)(lds + (bufoff) + ldsw + _i * 8192), 16, 0, 0); } while (0)
; #define PG8_LDA(dst, b, h) do { _Pragma("unroll") for (int m = 0; m < 4; ++m) _Pragma("unroll") for (int k = 0; k < 2; ++k) dst[m][k] = *(const LAS bf16x8*)(lds + PG8_SA(b, h) + aoff + m * 2048 + k * 1024); } while (0)
; #define PG8_LDB(dst, b, h) do { _Pragma("unroll") for (int n = 0; n < 2; ++n) _Pragma("unroll") for (int k = 0; k < 2; ++k) dst[n][k] = *(const LAS bf16x8*)(lds + PG8_SB(b, h) + boff + n * 2048 + k * 1024); } while (0)
; #define PG8_MMA(ai, bj, At, Bt) do { __builtin_amdgcn_s_setprio(1); _Pragma("unroll") for (int m = 0; m < 4; ++m) _Pragma("unroll") for (int n = 0; n < 2; ++n) _Pragma("unroll") for (int k = 0; k < 2; ++k) \
;         acc[ai][bj][m][n] = __builtin_amdgcn_mfma_f32_16x16x32_bf16(Bt[n][k], At[m][k], acc[ai][bj][m][n], 0, 0, 0); __builtin_amdgcn_s_setprio(0); } while (0)
; template <class Epi>
; __device__ __forceinline__ void gemm_phase(LAS unsigned char* lds, const Gemm g, const StaticOrder& S, const Epi& E, int wv) {
;     ...
;             PG8_WAIT_L(8); PG8_BAR; PG8_WAIT_L(0); PG8_MMA(0, 0, At, B0); PG8_BAR; PG8_SCHED;
;             PG8_LDB(B1, 0, 1); PG8_STAGE(PG8_SB(0, 0), b2, voffB);
;             PG8_BAR; PG8_WAIT_L(0); PG8_MMA(0, 1, At, B1); PG8_BAR;
;             PG8_LDA(At, 0, 1); PG8_STAGE(PG8_SA(0, 0), a2, voffA);
;             PG8_BAR; PG8_WAIT_L(0); PG8_MMA(1, 0, At, B0); PG8_BAR; PG8_SCHED;
;             PG8_STAGE(PG8_SB(0, 1), b2 + hstep, voffB);
;             PG8_WAIT_V(6); PG8_BAR; PG8_MMA(1, 1, At, B1); PG8_BAR;
;             PG8_LDB(B0, 1, 0); PG8_SCHED; PG8_LDA(At, 1, 0); PG8_STAGE(PG8_SA(0, 1), a2 + hstep, voffA);
;             PG8_WAIT_L(8); PG8_BAR; PG8_WAIT_L(0); PG8_MMA(0, 0, At, B0); PG8_BAR; PG8_SCHED;
;             PG8_LDB(B1, 1, 1); PG8_STAGE(PG8_SB(1, 0), b3, voffB);
;             PG8_BAR; PG8_WAIT_L(0); PG8_MMA(0, 1, At, B1); PG8_BAR;
;             PG8_LDA(At, 1, 1); PG8_STAGE(PG8_SA(1, 0), a3, voffA);
;             PG8_BAR; PG8_WAIT_L(0); PG8_MMA(1, 0, At, B0); PG8_BAR; PG8_SCHED;
;             PG8_STAGE(PG8_SB(1, 1), b3 + hstep, voffB);
;             PG8_WAIT_V(6); PG8_BAR; PG8_MMA(1, 1, At, B1); PG8_BAR;
	s_setprio 1
	v_mfma_f32_16x16x32_bf16 v[60:63], v[146:149], v[168:171], v[60:63]
	v_mfma_f32_16x16x32_bf16 v[56:59], v[160:163], v[168:171], v[56:59]
	v_mfma_f32_16x16x32_bf16 v[44:47], v[146:149], v[176:179], v[44:47]
	v_mfma_f32_16x16x32_bf16 v[40:43], v[160:163], v[176:179], v[40:43]
	v_mfma_f32_16x16x32_bf16 v[28:31], v[146:149], v[184:187], v[28:31]
	v_mfma_f32_16x16x32_bf16 v[24:27], v[160:163], v[184:187], v[24:27]
	v_mfma_f32_16x16x32_bf16 v[12:15], v[146:149], v[192:195], v[12:15]
	v_mfma_f32_16x16x32_bf16 v[8:11], v[160:163], v[192:195], v[8:11]
	v_mfma_f32_16x16x32_bf16 v[60:63], v[156:159], v[172:175], v[60:63]
	v_mfma_f32_16x16x32_bf16 v[56:59], v[164:167], v[172:175], v[56:59]
	v_mfma_f32_16x16x32_bf16 v[44:47], v[156:159], v[180:183], v[44:47]
	v_mfma_f32_16x16x32_bf16 v[40:43], v[164:167], v[180:183], v[40:43]
	v_mfma_f32_16x16x32_bf16 v[28:31], v[156:159], v[188:191], v[28:31]
	v_mfma_f32_16x16x32_bf16 v[24:27], v[164:167], v[188:191], v[24:27]
	v_mfma_f32_16x16x32_bf16 v[12:15], v[156:159], v[196:199], v[12:15]
	v_mfma_f32_16x16x32_bf16 v[8:11], v[164:167], v[196:199], v[8:11]
	v_mfma_f32_16x16x32_bf16 v[52:55], v[200:203], v[168:171], v[52:55]
	v_mfma_f32_16x16x32_bf16 v[48:51], v[208:211], v[168:171], v[48:51]
	v_mfma_f32_16x16x32_bf16 v[36:39], v[200:203], v[176:179], v[36:39]
	v_mfma_f32_16x16x32_bf16 v[32:35], v[208:211], v[176:179], v[32:35]
	v_mfma_f32_16x16x32_bf16 v[20:23], v[200:203], v[184:187], v[20:23]
	v_mfma_f32_16x16x32_bf16 v[16:19], v[208:211], v[184:187], v[16:19]
	v_mfma_f32_16x16x32_bf16 v[4:7], v[200:203], v[192:195], v[4:7]
	v_mfma_f32_16x16x32_bf16 v[0:3], v[208:211], v[192:195], v[0:3]
	v_mfma_f32_16x16x32_bf16 v[52:55], v[204:207], v[172:175], v[52:55]
	v_mfma_f32_16x16x32_bf16 v[48:51], v[212:215], v[172:175], v[48:51]
	v_mfma_f32_16x16x32_bf16 v[36:39], v[204:207], v[180:183], v[36:39]
	v_mfma_f32_16x16x32_bf16 v[32:35], v[212:215], v[180:183], v[32:35]
	v_mfma_f32_16x16x32_bf16 v[20:23], v[204:207], v[188:191], v[20:23]
	v_mfma_f32_16x16x32_bf16 v[16:19], v[212:215], v[188:191], v[16:19]
	v_mfma_f32_16x16x32_bf16 v[4:7], v[204:207], v[196:199], v[4:7]
	v_mfma_f32_16x16x32_bf16 v[0:3], v[212:215], v[196:199], v[0:3]
	s_setprio 0
	s_add_i32 s71, 0, 0x18000
	v_add_u32_e32 v136, s71, v152
	s_barrier
	ds_read_b128 v[146:149], v136
	ds_read_b128 v[156:159], v136 offset:1024
	ds_read_b128 v[160:163], v136 offset:2048
	ds_read_b128 v[164:167], v136 offset:3072
	s_add_u32 s40, s46, 0x40000
	s_addc_u32 s41, s47, 0
	ds_read_b128 v[168:171], v154 offset:32768
	ds_read_b128 v[172:175], v154 offset:33792
	ds_read_b128 v[176:179], v154 offset:34816
	ds_read_b128 v[180:183], v154 offset:35840
	ds_read_b128 v[184:187], v154 offset:36864
	ds_read_b128 v[188:191], v154 offset:37888
	ds_read_b128 v[192:195], v154 offset:38912
	ds_read_b128 v[196:199], v154 offset:39936
	s_mov_b32 m0, s52
	v_lshl_add_u64 v[252:253], s[40:41], 0, v[128:129]
	global_load_lds_dwordx4 v[252:253], off
	v_lshl_add_u64 v[252:253], s[40:41], 0, v[132:133]
	s_mov_b32 m0, s53
	s_nop 0
	global_load_lds_dwordx4 v[252:253], off
	s_add_i32 s46, 0, 0x1c000
	v_add_u32_e32 v136, s46, v152
	ds_read_b128 v[200:203], v136
	ds_read_b128 v[204:207], v136 offset:1024
	ds_read_b128 v[208:211], v136 offset:2048
	ds_read_b128 v[212:215], v136 offset:3072
	s_waitcnt vmcnt(8)
	s_waitcnt lgkmcnt(0)
	s_barrier
	s_setprio 1
	v_mfma_f32_16x16x32_bf16 v[124:127], v[146:149], v[168:171], v[124:127]
	v_mfma_f32_16x16x32_bf16 v[120:123], v[160:163], v[168:171], v[120:123]
	v_mfma_f32_16x16x32_bf16 v[108:111], v[146:149], v[176:179], v[108:111]
	v_mfma_f32_16x16x32_bf16 v[104:107], v[160:163], v[176:179], v[104:107]
	v_mfma_f32_16x16x32_bf16 v[92:95], v[146:149], v[184:187], v[92:95]
	v_mfma_f32_16x16x32_bf16 v[88:91], v[160:163], v[184:187], v[88:91]
	v_mfma_f32_16x16x32_bf16 v[76:79], v[146:149], v[192:195], v[76:79]
	v_mfma_f32_16x16x32_bf16 v[72:75], v[160:163], v[192:195], v[72:75]
	v_mfma_f32_16x16x32_bf16 v[124:127], v[156:159], v[172:175], v[124:127]
	v_mfma_f32_16x16x32_bf16 v[120:123], v[164:167], v[172:175], v[120:123]
	v_mfma_f32_16x16x32_bf16 v[108:111], v[156:159], v[180:183], v[108:111]
	v_mfma_f32_16x16x32_bf16 v[104:107], v[164:167], v[180:183], v[104:107]
	v_mfma_f32_16x16x32_bf16 v[92:95], v[156:159], v[188:191], v[92:95]
	v_mfma_f32_16x16x32_bf16 v[88:91], v[164:167], v[188:191], v[88:91]
	v_mfma_f32_16x16x32_bf16 v[76:79], v[156:159], v[196:199], v[76:79]
	v_mfma_f32_16x16x32_bf16 v[72:75], v[164:167], v[196:199], v[72:75]
	v_mfma_f32_16x16x32_bf16 v[116:119], v[200:203], v[168:171], v[116:119]
	v_mfma_f32_16x16x32_bf16 v[112:115], v[208:211], v[168:171], v[112:115]
	v_mfma_f32_16x16x32_bf16 v[100:103], v[200:203], v[176:179], v[100:103]
	v_mfma_f32_16x16x32_bf16 v[96:99], v[208:211], v[176:179], v[96:99]
	v_mfma_f32_16x16x32_bf16 v[84:87], v[200:203], v[184:187], v[84:87]
	v_mfma_f32_16x16x32_bf16 v[80:83], v[208:211], v[184:187], v[80:83]
	v_mfma_f32_16x16x32_bf16 v[68:71], v[200:203], v[192:195], v[68:71]
	v_mfma_f32_16x16x32_bf16 v[64:67], v[208:211], v[192:195], v[64:67]
	v_mfma_f32_16x16x32_bf16 v[116:119], v[204:207], v[172:175], v[116:119]
	v_mfma_f32_16x16x32_bf16 v[112:115], v[212:215], v[172:175], v[112:115]
	v_mfma_f32_16x16x32_bf16 v[100:103], v[204:207], v[180:183], v[100:103]
	v_mfma_f32_16x16x32_bf16 v[96:99], v[212:215], v[180:183], v[96:99]
	v_mfma_f32_16x16x32_bf16 v[84:87], v[204:207], v[188:191], v[84:87]
	v_mfma_f32_16x16x32_bf16 v[80:83], v[212:215], v[188:191], v[80:83]
	v_mfma_f32_16x16x32_bf16 v[68:71], v[204:207], v[196:199], v[68:71]
	v_mfma_f32_16x16x32_bf16 v[64:67], v[212:215], v[196:199], v[64:67]
	s_setprio 0
	s_barrier
; __device__ __forceinline__ int lane_fresh() { unsigned m = ~0u; asm volatile("" : "+s"(m)); return (int)__builtin_amdgcn_mbcnt_hi(m, __builtin_amdgcn_mbcnt_lo(m, 0u)); }
; #define PG8_WAIT_V(n) asm volatile("s_waitcnt vmcnt(" #n ")" ::: "memory")
; #define PG8_WAIT_L(n) asm volatile("s_waitcnt lgkmcnt(" #n ")" ::: "memory")
; template <class Epi>
; __device__ __forceinline__ void gemm_phase(LAS unsigned char* lds, const Gemm g, const StaticOrder& S, const Epi& E, int wv) {
;     ...
;             PG8_WAIT_V(6); PG8_BAR; PG8_MMA(1, 1, At, B1); PG8_BAR;
;             PG8_LDB(B0, 1, 0); PG8_SCHED; PG8_LDA(At, 1, 0); PG8_STAGE(PG8_SA(0, 1), a2 + hstep, voffA);
;             PG8_WAIT_L(8); PG8_BAR; PG8_WAIT_L(0); PG8_MMA(0, 0, At, B0); PG8_BAR; PG8_SCHED;
;             PG8_LDB(B1, 1, 1); PG8_STAGE(PG8_SB(1, 0), b3, voffB);
;             PG8_BAR; PG8_WAIT_L(0); PG8_MMA(0, 1, At, B1); PG8_BAR;
;             PG8_LDA(At, 1, 1); PG8_STAGE(PG8_SA(1, 0), a3, voffA);
;             PG8_BAR; PG8_WAIT_L(0); PG8_MMA(1, 0, At, B0); PG8_BAR; PG8_SCHED;
;             PG8_STAGE(PG8_SB(1, 1), b3 + hstep, voffB);
;             PG8_WAIT_V(6); PG8_BAR; PG8_MMA(1, 1, At, B1); PG8_BAR;
;         }
;         { const int ln2 = lane_fresh();
;           E(acc, cur, wr, wc, ln2 & 15, ln2 >> 4); }
;         if (!has_next) break;
;     __device__ __forceinline__ void operator()(const f32x4 (&acc)[2][2][4][2], const Unit& u, int wr, int wc, int fr, int fq) const {
;         const bool latent = u.pm < 128;
; #pragma unroll
;         for (int ai = 0; ai < 2; ++ai)
; #pragma unroll
;             for (int m = 0; m < 4; ++m) {
;                 const int row = u.pm * 256 + ai * 128 + wr * 64 + 4 * fr + m;
;                 const int t = row & (S - 1);
;                 const int pos = (wc & 1) ? (t & 63) : (t >> 6);
; #pragma unroll
;                 for (int bj = 0; bj < 2; ++bj) {
;                     const int col = u.pn * 256 + bj * 128 + wc * 32 + 4 * fq;
;                     f32x4 v0 = acc[ai][bj][m][0], v1 = acc[ai][bj][m][1];
;                     const bool rope = latent && (u.pn == 4 || u.pn == 5 || (u.pn == 6 && bj == 0));
;                     if (rope) {
;                         const f32x4 cs = *(const f32x4*)(cosT + pos * 16 + 4 * fq), sn = *(const f32x4*)(sinT + pos * 16 + 4 * fq);
;                         const f32x4 n0 = v0 * cs - v1 * sn, n1 = v1 * cs + v0 * sn; v0 = n0; v1 = n1;
	ds_read_b128 v[168:171], v154 offset:49152
	ds_read_b128 v[172:175], v154 offset:50176
	ds_read_b128 v[176:179], v154 offset:51200
	ds_read_b128 v[180:183], v154 offset:52224
	ds_read_b128 v[184:187], v154 offset:53248
	ds_read_b128 v[188:191], v154 offset:54272
	ds_read_b128 v[192:195], v154 offset:55296
	ds_read_b128 v[196:199], v154 offset:56320
	s_add_i32 s40, s71, s49
	v_lshl_add_u64 v[150:151], v[150:151], 0, s[28:29]
	s_mov_b32 m0, s40
	s_nop 0
	global_load_lds_dwordx4 v[150:151], off
	v_lshl_add_u64 v[150:151], v[216:217], 0, s[28:29]
	s_add_i32 m0, s40, 0x2000
	s_nop 0
	global_load_lds_dwordx4 v[150:151], off
	s_mov_b32 m0, s58
	v_lshl_add_u64 v[150:151], v[218:219], 0, s[28:29]
	global_load_lds_dwordx4 v[150:151], off
	v_lshl_add_u64 v[150:151], v[220:221], 0, s[28:29]
	s_mov_b32 m0, s59
	s_nop 0
	global_load_lds_dwordx4 v[150:151], off
	s_add_u32 s40, s44, 0x40080
	s_addc_u32 s41, s45, 0
	s_add_i32 s44, s46, s49
	v_lshl_add_u64 v[254:255], s[40:41], 0, v[130:131]
	s_mov_b32 m0, s44
	s_nop 0
	global_load_lds_dwordx4 v[254:255], off
	v_lshl_add_u64 v[254:255], s[40:41], 0, v[134:135]
	s_add_i32 m0, s44, 0x2000
	s_nop 0
	global_load_lds_dwordx4 v[254:255], off
	s_waitcnt vmcnt(8)
	s_waitcnt lgkmcnt(0)
	s_barrier
	s_setprio 1
	v_mfma_f32_16x16x32_bf16 v[60:63], v[146:149], v[168:171], v[60:63]
	v_mfma_f32_16x16x32_bf16 v[56:59], v[160:163], v[168:171], v[56:59]
	v_mfma_f32_16x16x32_bf16 v[44:47], v[146:149], v[176:179], v[44:47]
	v_mfma_f32_16x16x32_bf16 v[40:43], v[160:163], v[176:179], v[40:43]
	v_mfma_f32_16x16x32_bf16 v[28:31], v[146:149], v[184:187], v[28:31]
	v_mfma_f32_16x16x32_bf16 v[24:27], v[160:163], v[184:187], v[24:27]
	v_mfma_f32_16x16x32_bf16 v[12:15], v[146:149], v[192:195], v[12:15]
	v_mfma_f32_16x16x32_bf16 v[8:11], v[160:163], v[192:195], v[8:11]
	v_mfma_f32_16x16x32_bf16 v[60:63], v[156:159], v[172:175], v[60:63]
	v_mfma_f32_16x16x32_bf16 v[56:59], v[164:167], v[172:175], v[56:59]
	v_mfma_f32_16x16x32_bf16 v[44:47], v[156:159], v[180:183], v[44:47]
	v_mfma_f32_16x16x32_bf16 v[40:43], v[164:167], v[180:183], v[40:43]
	v_mfma_f32_16x16x32_bf16 v[28:31], v[156:159], v[188:191], v[28:31]
	v_mfma_f32_16x16x32_bf16 v[24:27], v[164:167], v[188:191], v[24:27]
	v_mfma_f32_16x16x32_bf16 v[12:15], v[156:159], v[196:199], v[12:15]
	v_mfma_f32_16x16x32_bf16 v[8:11], v[164:167], v[196:199], v[8:11]
	v_mfma_f32_16x16x32_bf16 v[52:55], v[200:203], v[168:171], v[52:55]
	v_mfma_f32_16x16x32_bf16 v[48:51], v[208:211], v[168:171], v[48:51]
	v_mfma_f32_16x16x32_bf16 v[36:39], v[200:203], v[176:179], v[36:39]
	v_mfma_f32_16x16x32_bf16 v[32:35], v[208:211], v[176:179], v[32:35]
	v_mfma_f32_16x16x32_bf16 v[20:23], v[200:203], v[184:187], v[20:23]
	v_mfma_f32_16x16x32_bf16 v[16:19], v[208:211], v[184:187], v[16:19]
	v_mfma_f32_16x16x32_bf16 v[4:7], v[200:203], v[192:195], v[4:7]
	v_mfma_f32_16x16x32_bf16 v[0:3], v[208:211], v[192:195], v[0:3]
	v_mfma_f32_16x16x32_bf16 v[52:55], v[204:207], v[172:175], v[52:55]
	v_mfma_f32_16x16x32_bf16 v[48:51], v[212:215], v[172:175], v[48:51]
	v_mfma_f32_16x16x32_bf16 v[36:39], v[204:207], v[180:183], v[36:39]
	v_mfma_f32_16x16x32_bf16 v[32:35], v[212:215], v[180:183], v[32:35]
	v_mfma_f32_16x16x32_bf16 v[20:23], v[204:207], v[188:191], v[20:23]
	v_mfma_f32_16x16x32_bf16 v[16:19], v[212:215], v[188:191], v[16:19]
	v_mfma_f32_16x16x32_bf16 v[4:7], v[204:207], v[196:199], v[4:7]
	v_mfma_f32_16x16x32_bf16 v[0:3], v[212:215], v[196:199], v[0:3]
	s_setprio 0
	s_add_i32 s70, s70, 2
	s_add_u32 s68, s68, 0x100
	s_addc_u32 s69, s69, 0
	s_cmp_gt_u32 s70, 13
	s_mov_b64 s[40:41], s[42:43]
	s_cbranch_scc0 .LBB0_215
	s_barrier
	s_cmpk_lt_i32 s6, 0x80
	s_cselect_b64 s[40:41], -1, 0
	s_lshl_b32 s31, s6, 8
	s_add_i32 s31, s31, s55
	s_mov_b32 s7, -1
	v_mbcnt_lo_u32_b32 v136, s7, 0
	v_mbcnt_hi_u32_b32 v136, s7, v136
	s_add_i32 s6, s8, -4
	s_cmp_lt_u32 s6, 3
	s_cselect_b64 s[6:7], -1, 0
	s_and_b64 s[42:43], s[40:41], s[6:7]
	s_and_b32 s9, s8, -2
	s_cmp_eq_u32 s9, 4
	s_cselect_b64 s[6:7], -1, 0
	s_and_b64 s[40:41], s[40:41], s[6:7]
	v_lshlrev_b32_e32 v146, 2, v136
	v_and_b32_e32 v156, 60, v146
	v_lshrrev_b32_e32 v147, 2, v136
	v_and_b32_e32 v148, 28, v147
	v_bfe_u32 v222, v136, 5, 1
	v_bfe_u32 v223, v136, 4, 1
	v_lshlrev_b32_e32 v222, 4, v222
	v_lshl_or_b32 v222, v223, 5, v222
	s_lshl_b32 s9, s8, 8
	s_or_b32 s9, s9, s57
	s_lshl_b32 s9, s9, 1
	v_add_u32_e32 v222, s9, v222
	v_or_b32_e32 v157, s31, v156
	v_mul_lo_u32 v150, v157, s67
	v_add_u32_e32 v150, v150, v222
	v_mov_b32_e32 v151, 0
	v_lshl_add_u64 v[224:225], s[18:19], 0, v[150:151]
	s_mov_b64 s[6:7], 0x1c00
	v_lshl_add_u64 v[226:227], v[224:225], 0, s[6:7]
	s_mov_b64 s[6:7], 0x70000
	v_lshl_add_u64 v[228:229], v[224:225], 0, s[6:7]
	s_mov_b64 s[6:7], 0x71c00
	v_lshl_add_u64 v[230:231], v[224:225], 0, s[6:7]
	s_and_b64 vcc, exec, s[42:43]
	s_cbranch_vccz .Lproj_norope
	s_bfe_u32 s35, s31, 0x80006
	s_add_i32 s9, s31, 0x80
	s_bfe_u32 s9, s9, 0x80006
	v_lshlrev_b32_e32 v232, 2, v148
	v_mov_b32_e32 v234, s35
	v_cndmask_b32_e64 v240, v156, v234, s[10:11]
	v_lshl_add_u32 v240, v240, 6, v232
	global_load_dwordx4 v[158:161], v240, s[22:23]
	global_load_dwordx4 v[162:165], v240, s[20:21]
	v_or_b32_e32 v241, 1, v156
	v_cndmask_b32_e64 v241, v241, v234, s[10:11]
	v_lshl_add_u32 v241, v241, 6, v232
	global_load_dwordx4 v[166:169], v241, s[22:23]
	global_load_dwordx4 v[170:173], v241, s[20:21]
	v_or_b32_e32 v242, 2, v156
	v_cndmask_b32_e64 v242, v242, v234, s[10:11]
	v_lshl_add_u32 v242, v242, 6, v232
	global_load_dwordx4 v[174:177], v242, s[22:23]
	global_load_dwordx4 v[178:181], v242, s[20:21]
	v_or_b32_e32 v243, 3, v156
	v_cndmask_b32_e64 v243, v243, v234, s[10:11]
	v_lshl_add_u32 v243, v243, 6, v232
	global_load_dwordx4 v[182:185], v243, s[22:23]
	global_load_dwordx4 v[186:189], v243, s[20:21]
	v_mov_b32_e32 v234, s9
	v_cndmask_b32_e64 v244, v156, v234, s[10:11]
	v_lshl_add_u32 v244, v244, 6, v232
	global_load_dwordx4 v[190:193], v244, s[22:23]
	global_load_dwordx4 v[194:197], v244, s[20:21]
	v_or_b32_e32 v245, 1, v156
	v_cndmask_b32_e64 v245, v245, v234, s[10:11]
	v_lshl_add_u32 v245, v245, 6, v232
	global_load_dwordx4 v[198:201], v245, s[22:23]
	global_load_dwordx4 v[202:205], v245, s[20:21]
	v_or_b32_e32 v246, 2, v156
	v_cndmask_b32_e64 v246, v246, v234, s[10:11]
	v_lshl_add_u32 v246, v246, 6, v232
	global_load_dwordx4 v[206:209], v246, s[22:23]
	global_load_dwordx4 v[210:213], v246, s[20:21]
	v_or_b32_e32 v247, 3, v156
	v_cndmask_b32_e64 v247, v247, v234, s[10:11]
	v_lshl_add_u32 v247, v247, 6, v232
	global_load_dwordx4 v[214:217], v247, s[22:23]
	global_load_dwordx4 v[218:221], v247, s[20:21]
	s_waitcnt vmcnt(0)

; #define PG8_STAGE(bufoff, gbase, voff) do { _Pragma("unroll") for (int _i = 0; _i < 2; ++_i) \
;         __builtin_amdgcn_global_load_lds((const unsigned*)((const char*)(gbase) + (voff)[_i]), (LAS unsigned*)(lds + (bufoff) + ldsw + _i * 8192), 16, 0, 0); } while (0)
; #define PG8_LDA(dst, b, h) do { _Pragma("unroll") for (int m = 0; m < 4; ++m) _Pragma("unroll") for (int k = 0; k < 2; ++k) dst[m][k] = *(const LAS bf16x8*)(lds + PG8_SA(b, h) + aoff + m * 2048 + k * 1024); } while (0)
; #define PG8_LDB(dst, b, h) do { _Pragma("unroll") for (int n = 0; n < 2; ++n) _Pragma("unroll") for (int k = 0; k < 2; ++k) dst[n][k] = *(const LAS bf16x8*)(lds + PG8_SB(b, h) + boff + n * 2048 + k * 1024); } while (0)
; #define PG8_MMA(ai, bj, At, Bt) do { __builtin_amdgcn_s_setprio(1); _Pragma("unroll") for (int m = 0; m < 4; ++m) _Pragma("unroll") for (int n = 0; n < 2; ++n) _Pragma("unroll") for (int k = 0; k < 2; ++k) \
;         acc[ai][bj][m][n] = __builtin_amdgcn_mfma_f32_16x16x32_bf16(Bt[n][k], At[m][k], acc[ai][bj][m][n], 0, 0, 0); __builtin_amdgcn_s_setprio(0); } while (0)
; #define PG8_WAIT_L(n) asm volatile("s_waitcnt lgkmcnt(" #n ")" ::: "memory")
; #define PG8_BAR __builtin_amdgcn_s_barrier()
; #define PG8_SCHED __builtin_amdgcn_sched_barrier(0)
; template <class Epi>
; __device__ __forceinline__ void gemm_phase(LAS unsigned char* lds, const Gemm g, const StaticOrder& S, const Epi& E, int wv) {
;     ...
;         for (int t = 0; t < nt; t += 2) {
;             const bool last = (t == nt - 2);
;             const char* a1 = cA + (size_t)(t + 1) * kstep;
;             const char* a2 = last ? nA : cA + (size_t)(t + 2) * kstep; const char* b2 = last ? nB : cB + (size_t)(t + 2) * kstep;
;             const char* a3 = a2 + kstep; const char* b3 = b2 + kstep;
;             PG8_LDB(B0, 0, 0); PG8_SCHED; PG8_LDA(At, 0, 0); PG8_STAGE(PG8_SA(1, 1), a1 + hstep, voffA);
;             PG8_WAIT_L(8); PG8_BAR; PG8_WAIT_L(0); PG8_MMA(0, 0, At, B0); PG8_BAR; PG8_SCHED;
;             PG8_LDB(B1, 0, 1); PG8_STAGE(PG8_SB(0, 0), b2, voffB);
;             PG8_BAR; PG8_WAIT_L(0); PG8_MMA(0, 1, At, B1); PG8_BAR;
;             PG8_LDA(At, 0, 1); PG8_STAGE(PG8_SA(0, 0), a2, voffA);
;             PG8_BAR; PG8_WAIT_L(0); PG8_MMA(1, 0, At, B0); PG8_BAR; PG8_SCHED;
.LBB0_846:
	s_barrier
	ds_read_b128 v[128:131], v165
	ds_read_b128 v[132:135], v165 offset:1024
	ds_read_b128 v[136:139], v165 offset:2048
	ds_read_b128 v[140:143], v165 offset:3072
	s_add_u32 s46, s44, 0x100
	s_addc_u32 s47, s45, 0
	s_cmp_eq_u32 s82, 12
	s_cselect_b32 s51, s37, s47
	s_cselect_b32 s50, s43, s46
	s_cselect_b32 s49, s35, s81
	s_cselect_b32 s48, s79, s80
	ds_read_b128 v[168:171], v166
	ds_read_b128 v[172:175], v166 offset:1024
	ds_read_b128 v[176:179], v166 offset:2048
	ds_read_b128 v[180:183], v166 offset:3072
	ds_read_b128 v[184:187], v166 offset:4096
	ds_read_b128 v[188:191], v166 offset:5120
	ds_read_b128 v[192:195], v166 offset:6144
	ds_read_b128 v[196:199], v166 offset:7168
	ds_read_b128 v[200:203], v167
	ds_read_b128 v[204:207], v167 offset:1024
	ds_read_b128 v[208:211], v167 offset:2048
	ds_read_b128 v[212:215], v167 offset:3072
	v_lshl_add_u64 v[252:253], s[44:45], 0, v[154:155]
	s_add_i32 m0, s59, 0xc000
	s_nop 0
	global_load_lds_dwordx4 v[252:253], off
	v_lshl_add_u64 v[252:253], s[44:45], 0, v[156:157]
	s_add_i32 m0, s59, 0xe000
	s_nop 0
	global_load_lds_dwordx4 v[252:253], off
	s_waitcnt vmcnt(8)
	s_waitcnt lgkmcnt(0)
	s_barrier
	s_setprio 1
	v_mfma_f32_16x16x32_bf16 v[124:127], v[128:131], v[168:171], v[124:127]
	v_mfma_f32_16x16x32_bf16 v[120:123], v[136:139], v[168:171], v[120:123]
	v_mfma_f32_16x16x32_bf16 v[116:119], v[128:131], v[176:179], v[116:119]
	v_mfma_f32_16x16x32_bf16 v[112:115], v[136:139], v[176:179], v[112:115]
	v_mfma_f32_16x16x32_bf16 v[108:111], v[128:131], v[184:187], v[108:111]
	v_mfma_f32_16x16x32_bf16 v[96:99], v[136:139], v[184:187], v[96:99]
	v_mfma_f32_16x16x32_bf16 v[80:83], v[128:131], v[192:195], v[80:83]
	v_mfma_f32_16x16x32_bf16 v[72:75], v[136:139], v[192:195], v[72:75]
	v_mfma_f32_16x16x32_bf16 v[124:127], v[132:135], v[172:175], v[124:127]
	v_mfma_f32_16x16x32_bf16 v[120:123], v[140:143], v[172:175], v[120:123]
	v_mfma_f32_16x16x32_bf16 v[116:119], v[132:135], v[180:183], v[116:119]
	v_mfma_f32_16x16x32_bf16 v[112:115], v[140:143], v[180:183], v[112:115]
	v_mfma_f32_16x16x32_bf16 v[108:111], v[132:135], v[188:191], v[108:111]
	v_mfma_f32_16x16x32_bf16 v[96:99], v[140:143], v[188:191], v[96:99]
	v_mfma_f32_16x16x32_bf16 v[80:83], v[132:135], v[196:199], v[80:83]
	v_mfma_f32_16x16x32_bf16 v[72:75], v[140:143], v[196:199], v[72:75]
	v_mfma_f32_16x16x32_bf16 v[104:107], v[200:203], v[168:171], v[104:107]
	v_mfma_f32_16x16x32_bf16 v[100:103], v[208:211], v[168:171], v[100:103]
	v_mfma_f32_16x16x32_bf16 v[92:95], v[200:203], v[176:179], v[92:95]
	v_mfma_f32_16x16x32_bf16 v[88:91], v[208:211], v[176:179], v[88:91]
	v_mfma_f32_16x16x32_bf16 v[84:87], v[200:203], v[184:187], v[84:87]
	v_mfma_f32_16x16x32_bf16 v[76:79], v[208:211], v[184:187], v[76:79]
	v_mfma_f32_16x16x32_bf16 v[68:71], v[200:203], v[192:195], v[68:71]
	v_mfma_f32_16x16x32_bf16 v[64:67], v[208:211], v[192:195], v[64:67]
	v_mfma_f32_16x16x32_bf16 v[104:107], v[204:207], v[172:175], v[104:107]
	v_mfma_f32_16x16x32_bf16 v[100:103], v[212:215], v[172:175], v[100:103]
	v_mfma_f32_16x16x32_bf16 v[92:95], v[204:207], v[180:183], v[92:95]
	v_mfma_f32_16x16x32_bf16 v[88:91], v[212:215], v[180:183], v[88:91]
	v_mfma_f32_16x16x32_bf16 v[84:87], v[204:207], v[188:191], v[84:87]
	v_mfma_f32_16x16x32_bf16 v[76:79], v[212:215], v[188:191], v[76:79]
	v_mfma_f32_16x16x32_bf16 v[68:71], v[204:207], v[196:199], v[68:71]
	v_mfma_f32_16x16x32_bf16 v[64:67], v[212:215], v[196:199], v[64:67]
	s_setprio 0
	s_barrier
	ds_read_b128 v[168:171], v166 offset:16384
	ds_read_b128 v[172:175], v166 offset:17408
	ds_read_b128 v[176:179], v166 offset:18432
	ds_read_b128 v[180:183], v166 offset:19456
	ds_read_b128 v[184:187], v166 offset:20480
	ds_read_b128 v[188:191], v166 offset:21504
	ds_read_b128 v[192:195], v166 offset:22528
	ds_read_b128 v[196:199], v166 offset:23552
	s_add_i32 s44, s72, s58
	v_lshl_add_u64 v[162:163], s[48:49], 0, v[146:147]
	s_mov_b32 m0, s44
	s_nop 0
	global_load_lds_dwordx4 v[162:163], off
	v_lshl_add_u64 v[216:217], s[48:49], 0, v[150:151]
	s_add_i32 m0, s44, 0x2000
	s_nop 0
	global_load_lds_dwordx4 v[216:217], off
	s_mov_b32 m0, s59
	v_lshl_add_u64 v[218:219], s[50:51], 0, v[144:145]
	global_load_lds_dwordx4 v[218:219], off
	v_lshl_add_u64 v[220:221], s[50:51], 0, v[148:149]
	s_mov_b32 m0, s60
	s_nop 0
	global_load_lds_dwordx4 v[220:221], off
	s_add_u32 s44, s48, 0x40000
	s_addc_u32 s45, s49, 0
	s_add_i32 s83, s73, s58
	v_lshl_add_u64 v[254:255], s[44:45], 0, v[146:147]
	s_mov_b32 m0, s83
	s_nop 0
	global_load_lds_dwordx4 v[254:255], off
	v_lshl_add_u64 v[254:255], s[44:45], 0, v[150:151]
	s_add_i32 m0, s83, 0x2000
	s_nop 0
	global_load_lds_dwordx4 v[254:255], off
	s_waitcnt vmcnt(8)
	s_waitcnt lgkmcnt(0)
	s_barrier
; #define PG8_STAGE(bufoff, gbase, voff) do { _Pragma("unroll") for (int _i = 0; _i < 2; ++_i) \
;         __builtin_amdgcn_global_load_lds((const unsigned*)((const char*)(gbase) + (voff)[_i]), (LAS unsigned*)(lds + (bufoff) + ldsw + _i * 8192), 16, 0, 0); } while (0)
; #define PG8_LDA(dst, b, h) do { _Pragma("unroll") for (int m = 0; m < 4; ++m) _Pragma("unroll") for (int k = 0; k < 2; ++k) dst[m][k] = *(const LAS bf16x8*)(lds + PG8_SA(b, h) + aoff + m * 2048 + k * 1024); } while (0)
; #define PG8_LDB(dst, b, h) do { _Pragma("unroll") for (int n = 0; n < 2; ++n) _Pragma("unroll") for (int k = 0; k < 2; ++k) dst[n][k] = *(const LAS bf16x8*)(lds + PG8_SB(b, h) + boff + n * 2048 + k * 1024); } while (0)
; #define PG8_MMA(ai, bj, At, Bt) do { __builtin_amdgcn_s_setprio(1); _Pragma("unroll") for (int m = 0; m < 4; ++m) _Pragma("unroll") for (int n = 0; n < 2; ++n) _Pragma("unroll") for (int k = 0; k < 2; ++k) \
;         acc[ai][bj][m][n] = __builtin_amdgcn_mfma_f32_16x16x32_bf16(Bt[n][k], At[m][k], acc[ai][bj][m][n], 0, 0, 0); __builtin_amdgcn_s_setprio(0); } while (0)
; template <class Epi>
; __device__ __forceinline__ void gemm_phase(LAS unsigned char* lds, const Gemm g, const StaticOrder& S, const Epi& E, int wv) {
;     ...
;             PG8_WAIT_L(8); PG8_BAR; PG8_WAIT_L(0); PG8_MMA(0, 0, At, B0); PG8_BAR; PG8_SCHED;
;             PG8_LDB(B1, 0, 1); PG8_STAGE(PG8_SB(0, 0), b2, voffB);
;             PG8_BAR; PG8_WAIT_L(0); PG8_MMA(0, 1, At, B1); PG8_BAR;
;             PG8_LDA(At, 0, 1); PG8_STAGE(PG8_SA(0, 0), a2, voffA);
;             PG8_BAR; PG8_WAIT_L(0); PG8_MMA(1, 0, At, B0); PG8_BAR; PG8_SCHED;
;             PG8_STAGE(PG8_SB(0, 1), b2 + hstep, voffB);
;             PG8_WAIT_V(6); PG8_BAR; PG8_MMA(1, 1, At, B1); PG8_BAR;
;             PG8_LDB(B0, 1, 0); PG8_SCHED; PG8_LDA(At, 1, 0); PG8_STAGE(PG8_SA(0, 1), a2 + hstep, voffA);
;             PG8_WAIT_L(8); PG8_BAR; PG8_WAIT_L(0); PG8_MMA(0, 0, At, B0); PG8_BAR; PG8_SCHED;
;             PG8_LDB(B1, 1, 1); PG8_STAGE(PG8_SB(1, 0), b3, voffB);
;             PG8_BAR; PG8_WAIT_L(0); PG8_MMA(0, 1, At, B1); PG8_BAR;
;             PG8_LDA(At, 1, 1); PG8_STAGE(PG8_SA(1, 0), a3, voffA);
;             PG8_BAR; PG8_WAIT_L(0); PG8_MMA(1, 0, At, B0); PG8_BAR; PG8_SCHED;
;             PG8_STAGE(PG8_SB(1, 1), b3 + hstep, voffB);
;             PG8_WAIT_V(6); PG8_BAR; PG8_MMA(1, 1, At, B1); PG8_BAR;
	s_setprio 1
	v_mfma_f32_16x16x32_bf16 v[60:63], v[128:131], v[168:171], v[60:63]
	v_mfma_f32_16x16x32_bf16 v[56:59], v[136:139], v[168:171], v[56:59]
	v_mfma_f32_16x16x32_bf16 v[48:51], v[128:131], v[176:179], v[48:51]
	v_mfma_f32_16x16x32_bf16 v[40:43], v[136:139], v[176:179], v[40:43]
	v_mfma_f32_16x16x32_bf16 v[32:35], v[128:131], v[184:187], v[32:35]
	v_mfma_f32_16x16x32_bf16 v[24:27], v[136:139], v[184:187], v[24:27]
	v_mfma_f32_16x16x32_bf16 v[16:19], v[128:131], v[192:195], v[16:19]
	v_mfma_f32_16x16x32_bf16 v[8:11], v[136:139], v[192:195], v[8:11]
	v_mfma_f32_16x16x32_bf16 v[60:63], v[132:135], v[172:175], v[60:63]
	v_mfma_f32_16x16x32_bf16 v[56:59], v[140:143], v[172:175], v[56:59]
	v_mfma_f32_16x16x32_bf16 v[48:51], v[132:135], v[180:183], v[48:51]
	v_mfma_f32_16x16x32_bf16 v[40:43], v[140:143], v[180:183], v[40:43]
	v_mfma_f32_16x16x32_bf16 v[32:35], v[132:135], v[188:191], v[32:35]
	v_mfma_f32_16x16x32_bf16 v[24:27], v[140:143], v[188:191], v[24:27]
	v_mfma_f32_16x16x32_bf16 v[16:19], v[132:135], v[196:199], v[16:19]
	v_mfma_f32_16x16x32_bf16 v[8:11], v[140:143], v[196:199], v[8:11]
	v_mfma_f32_16x16x32_bf16 v[52:55], v[200:203], v[168:171], v[52:55]
	v_mfma_f32_16x16x32_bf16 v[44:47], v[208:211], v[168:171], v[44:47]
	v_mfma_f32_16x16x32_bf16 v[36:39], v[200:203], v[176:179], v[36:39]
	v_mfma_f32_16x16x32_bf16 v[28:31], v[208:211], v[176:179], v[28:31]
	v_mfma_f32_16x16x32_bf16 v[20:23], v[200:203], v[184:187], v[20:23]
	v_mfma_f32_16x16x32_bf16 v[12:15], v[208:211], v[184:187], v[12:15]
	v_mfma_f32_16x16x32_bf16 v[4:7], v[200:203], v[192:195], v[4:7]
	v_mfma_f32_16x16x32_bf16 v[0:3], v[208:211], v[192:195], v[0:3]
	v_mfma_f32_16x16x32_bf16 v[52:55], v[204:207], v[172:175], v[52:55]
	v_mfma_f32_16x16x32_bf16 v[44:47], v[212:215], v[172:175], v[44:47]
	v_mfma_f32_16x16x32_bf16 v[36:39], v[204:207], v[180:183], v[36:39]
	v_mfma_f32_16x16x32_bf16 v[28:31], v[212:215], v[180:183], v[28:31]
	v_mfma_f32_16x16x32_bf16 v[20:23], v[204:207], v[188:191], v[20:23]
	v_mfma_f32_16x16x32_bf16 v[12:15], v[212:215], v[188:191], v[12:15]
	v_mfma_f32_16x16x32_bf16 v[4:7], v[204:207], v[196:199], v[4:7]
	v_mfma_f32_16x16x32_bf16 v[0:3], v[212:215], v[196:199], v[0:3]
	s_setprio 0
	s_add_i32 s83, 0, 0x18000
	v_add_u32_e32 v140, s83, v164
	s_barrier
	ds_read_b128 v[128:131], v140
	ds_read_b128 v[132:135], v140 offset:1024
	ds_read_b128 v[136:139], v140 offset:2048
	ds_read_b128 v[140:143], v140 offset:3072
	s_add_u32 s44, s50, 0x40000
	s_addc_u32 s45, s51, 0
	ds_read_b128 v[168:171], v166 offset:32768
	ds_read_b128 v[172:175], v166 offset:33792
	ds_read_b128 v[176:179], v166 offset:34816
	ds_read_b128 v[180:183], v166 offset:35840
	ds_read_b128 v[184:187], v166 offset:36864
	ds_read_b128 v[188:191], v166 offset:37888
	ds_read_b128 v[192:195], v166 offset:38912
	ds_read_b128 v[196:199], v166 offset:39936
	s_mov_b32 m0, s61
	v_lshl_add_u64 v[252:253], s[44:45], 0, v[144:145]
	global_load_lds_dwordx4 v[252:253], off
	v_lshl_add_u64 v[252:253], s[44:45], 0, v[148:149]
	s_mov_b32 m0, s64
	s_nop 0
	global_load_lds_dwordx4 v[252:253], off
	s_add_i32 s50, 0, 0x1c000
	v_add_u32_e32 v152, s50, v164
	ds_read_b128 v[200:203], v152
	ds_read_b128 v[204:207], v152 offset:1024
	ds_read_b128 v[208:211], v152 offset:2048
	ds_read_b128 v[212:215], v152 offset:3072
	s_waitcnt vmcnt(8)
	s_waitcnt lgkmcnt(0)
	s_barrier
	s_setprio 1
	v_mfma_f32_16x16x32_bf16 v[124:127], v[128:131], v[168:171], v[124:127]
	v_mfma_f32_16x16x32_bf16 v[120:123], v[136:139], v[168:171], v[120:123]
	v_mfma_f32_16x16x32_bf16 v[116:119], v[128:131], v[176:179], v[116:119]
	v_mfma_f32_16x16x32_bf16 v[112:115], v[136:139], v[176:179], v[112:115]
	v_mfma_f32_16x16x32_bf16 v[108:111], v[128:131], v[184:187], v[108:111]
	v_mfma_f32_16x16x32_bf16 v[96:99], v[136:139], v[184:187], v[96:99]
	v_mfma_f32_16x16x32_bf16 v[80:83], v[128:131], v[192:195], v[80:83]
	v_mfma_f32_16x16x32_bf16 v[72:75], v[136:139], v[192:195], v[72:75]
	v_mfma_f32_16x16x32_bf16 v[124:127], v[132:135], v[172:175], v[124:127]
	v_mfma_f32_16x16x32_bf16 v[120:123], v[140:143], v[172:175], v[120:123]
	v_mfma_f32_16x16x32_bf16 v[116:119], v[132:135], v[180:183], v[116:119]
	v_mfma_f32_16x16x32_bf16 v[112:115], v[140:143], v[180:183], v[112:115]
	v_mfma_f32_16x16x32_bf16 v[108:111], v[132:135], v[188:191], v[108:111]
	v_mfma_f32_16x16x32_bf16 v[96:99], v[140:143], v[188:191], v[96:99]
	v_mfma_f32_16x16x32_bf16 v[80:83], v[132:135], v[196:199], v[80:83]
	v_mfma_f32_16x16x32_bf16 v[72:75], v[140:143], v[196:199], v[72:75]
	v_mfma_f32_16x16x32_bf16 v[104:107], v[200:203], v[168:171], v[104:107]
	v_mfma_f32_16x16x32_bf16 v[100:103], v[208:211], v[168:171], v[100:103]
	v_mfma_f32_16x16x32_bf16 v[92:95], v[200:203], v[176:179], v[92:95]
	v_mfma_f32_16x16x32_bf16 v[88:91], v[208:211], v[176:179], v[88:91]
	v_mfma_f32_16x16x32_bf16 v[84:87], v[200:203], v[184:187], v[84:87]
	v_mfma_f32_16x16x32_bf16 v[76:79], v[208:211], v[184:187], v[76:79]
	v_mfma_f32_16x16x32_bf16 v[68:71], v[200:203], v[192:195], v[68:71]
	v_mfma_f32_16x16x32_bf16 v[64:67], v[208:211], v[192:195], v[64:67]
	v_mfma_f32_16x16x32_bf16 v[104:107], v[204:207], v[172:175], v[104:107]
	v_mfma_f32_16x16x32_bf16 v[100:103], v[212:215], v[172:175], v[100:103]
	v_mfma_f32_16x16x32_bf16 v[92:95], v[204:207], v[180:183], v[92:95]
	v_mfma_f32_16x16x32_bf16 v[88:91], v[212:215], v[180:183], v[88:91]
	v_mfma_f32_16x16x32_bf16 v[84:87], v[204:207], v[188:191], v[84:87]
	v_mfma_f32_16x16x32_bf16 v[76:79], v[212:215], v[188:191], v[76:79]
	v_mfma_f32_16x16x32_bf16 v[68:71], v[204:207], v[196:199], v[68:71]
	v_mfma_f32_16x16x32_bf16 v[64:67], v[212:215], v[196:199], v[64:67]
	s_setprio 0
	s_barrier
; __device__ __forceinline__ int lane_fresh() { unsigned m = ~0u; asm volatile("" : "+s"(m)); return (int)__builtin_amdgcn_mbcnt_hi(m, __builtin_amdgcn_mbcnt_lo(m, 0u)); }
; __device__ __forceinline__ unsigned pk2(float lo, float hi) { unsigned r; asm("v_cvt_pk_bf16_f32 %0, %1, %2" : "=v"(r) : "v"(lo), "v"(hi)); return r; }
; #define PG8_LDA(dst, b, h) do { _Pragma("unroll") for (int m = 0; m < 4; ++m) _Pragma("unroll") for (int k = 0; k < 2; ++k) dst[m][k] = *(const LAS bf16x8*)(lds + PG8_SA(b, h) + aoff + m * 2048 + k * 1024); } while (0)
; template <class Epi>
; __device__ __forceinline__ void gemm_phase(LAS unsigned char* lds, const Gemm g, const StaticOrder& S, const Epi& E, int wv) {
;     ...
;             PG8_WAIT_L(8); PG8_BAR; PG8_WAIT_L(0); PG8_MMA(0, 0, At, B0); PG8_BAR; PG8_SCHED;
;             PG8_LDB(B1, 1, 1); PG8_STAGE(PG8_SB(1, 0), b3, voffB);
;             PG8_BAR; PG8_WAIT_L(0); PG8_MMA(0, 1, At, B1); PG8_BAR;
;             PG8_LDA(At, 1, 1); PG8_STAGE(PG8_SA(1, 0), a3, voffA);
;             PG8_BAR; PG8_WAIT_L(0); PG8_MMA(1, 0, At, B0); PG8_BAR; PG8_SCHED;
;             PG8_STAGE(PG8_SB(1, 1), b3 + hstep, voffB);
;             PG8_WAIT_V(6); PG8_BAR; PG8_MMA(1, 1, At, B1); PG8_BAR;
;         }
;         { const int ln2 = lane_fresh();
;           E(acc, cur, wr, wc, ln2 & 15, ln2 >> 4); }
;         if (!has_next) break;
;     __device__ __forceinline__ void operator()(const f32x4 (&acc)[2][2][4][2], const Unit& u, int wr, int wc, int fr, int fq) const {
;         const float* gate = (u.pm >= 64) ? gate1 : gate0;
;         f32x4 gv[2][2];
; #pragma unroll
;         for (int bj = 0; bj < 2; ++bj)
; #pragma unroll
;             for (int n = 0; n < 2; ++n) gv[bj][n] = *(const f32x4*)(gate + u.pn * 256 + bj * 128 + wc * 32 + n * 16 + 4 * fq);
; #pragma unroll
;         for (int ai = 0; ai < 2; ++ai)
; #pragma unroll
;             for (int m = 0; m < 4; ++m) {
;                 const size_t row = (size_t)u.pm * 256 + ai * 128 + wr * 64 + 4 * fr + m;
; #pragma unroll
;                 for (int bj = 0; bj < 2; ++bj)
; #pragma unroll
;                     for (int n = 0; n < 2; ++n) {
;                         const f32x4 v = gv[bj][n] * acc[ai][bj][m][n];
;                         u32x2 w; w.x = pk2(v[0], v[1]); w.y = pk2(v[2], v[3]);
;                         *(u32x2*)(O + row * D + u.pn * 256 + bj * 128 + wc * 32 + n * 16 + 4 * fq) = w;
	ds_read_b128 v[168:171], v166 offset:49152
	ds_read_b128 v[172:175], v166 offset:50176
	ds_read_b128 v[176:179], v166 offset:51200
	ds_read_b128 v[180:183], v166 offset:52224
	ds_read_b128 v[184:187], v166 offset:53248
	ds_read_b128 v[188:191], v166 offset:54272
	ds_read_b128 v[192:195], v166 offset:55296
	ds_read_b128 v[196:199], v166 offset:56320
	s_add_i32 s44, s83, s58
	v_lshl_add_u64 v[162:163], v[162:163], 0, s[16:17]
	s_mov_b32 m0, s44
	s_nop 0
	global_load_lds_dwordx4 v[162:163], off
	v_lshl_add_u64 v[162:163], v[216:217], 0, s[16:17]
	s_add_i32 m0, s44, 0x2000
	s_nop 0
	global_load_lds_dwordx4 v[162:163], off
	s_mov_b32 m0, s67
	v_lshl_add_u64 v[162:163], v[218:219], 0, s[16:17]
	global_load_lds_dwordx4 v[162:163], off
	v_lshl_add_u64 v[162:163], v[220:221], 0, s[16:17]
	s_mov_b32 m0, s68
	s_nop 0
	global_load_lds_dwordx4 v[162:163], off
	s_add_u32 s44, s48, 0x40080
	s_addc_u32 s45, s49, 0
	s_add_i32 s48, s50, s58
	v_lshl_add_u64 v[254:255], s[44:45], 0, v[146:147]
	s_mov_b32 m0, s48
	s_nop 0
	global_load_lds_dwordx4 v[254:255], off
	v_lshl_add_u64 v[254:255], s[44:45], 0, v[150:151]
	s_add_i32 m0, s48, 0x2000
	s_nop 0
	global_load_lds_dwordx4 v[254:255], off
	s_waitcnt vmcnt(8)
	s_waitcnt lgkmcnt(0)
	s_barrier
	s_setprio 1
	v_mfma_f32_16x16x32_bf16 v[60:63], v[128:131], v[168:171], v[60:63]
	v_mfma_f32_16x16x32_bf16 v[56:59], v[136:139], v[168:171], v[56:59]
	v_mfma_f32_16x16x32_bf16 v[48:51], v[128:131], v[176:179], v[48:51]
	v_mfma_f32_16x16x32_bf16 v[40:43], v[136:139], v[176:179], v[40:43]
	v_mfma_f32_16x16x32_bf16 v[32:35], v[128:131], v[184:187], v[32:35]
	v_mfma_f32_16x16x32_bf16 v[24:27], v[136:139], v[184:187], v[24:27]
	v_mfma_f32_16x16x32_bf16 v[16:19], v[128:131], v[192:195], v[16:19]
	v_mfma_f32_16x16x32_bf16 v[8:11], v[136:139], v[192:195], v[8:11]
	v_mfma_f32_16x16x32_bf16 v[60:63], v[132:135], v[172:175], v[60:63]
	v_mfma_f32_16x16x32_bf16 v[56:59], v[140:143], v[172:175], v[56:59]
	v_mfma_f32_16x16x32_bf16 v[48:51], v[132:135], v[180:183], v[48:51]
	v_mfma_f32_16x16x32_bf16 v[40:43], v[140:143], v[180:183], v[40:43]
	v_mfma_f32_16x16x32_bf16 v[32:35], v[132:135], v[188:191], v[32:35]
	v_mfma_f32_16x16x32_bf16 v[24:27], v[140:143], v[188:191], v[24:27]
	v_mfma_f32_16x16x32_bf16 v[16:19], v[132:135], v[196:199], v[16:19]
	v_mfma_f32_16x16x32_bf16 v[8:11], v[140:143], v[196:199], v[8:11]
	v_mfma_f32_16x16x32_bf16 v[52:55], v[200:203], v[168:171], v[52:55]
	v_mfma_f32_16x16x32_bf16 v[44:47], v[208:211], v[168:171], v[44:47]
	v_mfma_f32_16x16x32_bf16 v[36:39], v[200:203], v[176:179], v[36:39]
	v_mfma_f32_16x16x32_bf16 v[28:31], v[208:211], v[176:179], v[28:31]
	v_mfma_f32_16x16x32_bf16 v[20:23], v[200:203], v[184:187], v[20:23]
	v_mfma_f32_16x16x32_bf16 v[12:15], v[208:211], v[184:187], v[12:15]
	v_mfma_f32_16x16x32_bf16 v[4:7], v[200:203], v[192:195], v[4:7]
	v_mfma_f32_16x16x32_bf16 v[0:3], v[208:211], v[192:195], v[0:3]
	v_mfma_f32_16x16x32_bf16 v[52:55], v[204:207], v[172:175], v[52:55]
	v_mfma_f32_16x16x32_bf16 v[44:47], v[212:215], v[172:175], v[44:47]
	v_mfma_f32_16x16x32_bf16 v[36:39], v[204:207], v[180:183], v[36:39]
	v_mfma_f32_16x16x32_bf16 v[28:31], v[212:215], v[180:183], v[28:31]
	v_mfma_f32_16x16x32_bf16 v[20:23], v[204:207], v[188:191], v[20:23]
	v_mfma_f32_16x16x32_bf16 v[12:15], v[212:215], v[188:191], v[12:15]
	v_mfma_f32_16x16x32_bf16 v[4:7], v[204:207], v[196:199], v[4:7]
	v_mfma_f32_16x16x32_bf16 v[0:3], v[212:215], v[196:199], v[0:3]
	s_setprio 0
	s_add_i32 s82, s82, 2
	s_add_u32 s80, s80, 0x100
	s_addc_u32 s81, s81, 0
	s_cmp_gt_u32 s82, 13
	s_mov_b64 s[44:45], s[46:47]
	s_cbranch_scc0 .LBB0_846
	s_barrier
	s_mov_b32 s35, -1
	s_cmp_gt_i32 s42, 63
	v_mbcnt_lo_u32_b32 v128, s35, 0
	v_mbcnt_hi_u32_b32 v152, s35, v128
	s_cselect_b32 s35, s74, 0x1642000
	s_add_u32 s35, s6, s35
	s_addc_u32 s37, s7, 0
	s_lshl_b32 s44, s8, 8
	s_ashr_i32 s45, s44, 31
	s_lshl_b64 s[46:47], s[44:45], 2
	s_add_u32 s8, s35, s46
	s_addc_u32 s35, s37, s47
	s_lshl_b32 s37, s66, 2
	v_lshrrev_b32_e32 v128, 2, v152
	s_add_u32 s46, s8, s37
	v_and_b32_e32 v162, 28, v128
	s_addc_u32 s47, s35, 0
	v_lshlrev_b32_e32 v128, 2, v162
	s_nop 0
	s_ashr_i32 s43, s42, 31
	s_lshl_b64 s[42:43], s[42:43], 8
	s_add_u32 s8, s42, s65
	v_lshlrev_b32_e32 v163, 2, v152
	s_addc_u32 s35, s43, s69
	v_bfe_u32 v222, v152, 5, 1
	v_bfe_u32 v152, v152, 4, 1
	v_lshlrev_b32_e32 v222, 4, v222
	v_lshl_or_b32 v152, v152, 5, v222
	v_and_or_b32 v162, v163, 60, s8
	v_mov_b32_e32 v163, s35
	v_lshlrev_b64 v[162:163], 11, v[162:163]
	v_lshl_add_u64 v[162:163], s[14:15], 0, v[162:163]
	s_lshl_b32 s8, s66, 1
	v_lshl_add_u64 v[162:163], s[44:45], 1, v[162:163]
	v_lshl_add_u64 v[162:163], v[162:163], 0, s[8:9]
	v_lshl_add_u64 v[162:163], v[162:163], 0, v[152:153]
	v_lshl_add_u64 v[168:169], v[162:163], 0, s[18:19]
	v_lshl_add_u64 v[170:171], v[162:163], 0, s[12:13]
	s_mov_b32 s8, s34
	s_nop 0
	v_lshl_add_u64 v[222:223], v[162:163], 0, s[28:29]
	s_mov_b32 s42, s36
	s_mov_b64 s[46:47], s[40:41]
	s_mov_b64 s[44:45], s[38:39]
	v_pk_mul_f32 v[124:125], v[124:125], v[236:237]
	v_pk_mul_f32 v[126:127], v[126:127], v[238:239]
	v_pk_mul_f32 v[120:121], v[120:121], v[232:233]
	v_pk_mul_f32 v[122:123], v[122:123], v[234:235]
	v_cvt_pk_bf16_f32 v124, v124, v125
	v_cvt_pk_bf16_f32 v125, v126, v127
	v_cvt_pk_bf16_f32 v126, v120, v121
	v_cvt_pk_bf16_f32 v127, v122, v123
	v_pk_mul_f32 v[104:105], v[104:105], v[228:229]
	v_pk_mul_f32 v[106:107], v[106:107], v[230:231]
	v_pk_mul_f32 v[100:101], v[100:101], v[224:225]
	v_pk_mul_f32 v[102:103], v[102:103], v[226:227]
	v_permlane16_swap_b32_e32 v124, v126
	v_permlane16_swap_b32_e32 v125, v127
	global_store_dwordx4 v[162:163], v[124:127], off
; __device__ __forceinline__ unsigned pk2(float lo, float hi) { unsigned r; asm("v_cvt_pk_bf16_f32 %0, %1, %2" : "=v"(r) : "v"(lo), "v"(hi)); return r; }
; #define PG8_WAIT_V(n) asm volatile("s_waitcnt vmcnt(" #n ")" ::: "memory")
; #define PG8_BAR __builtin_amdgcn_s_barrier()
; template <class Epi>
; __device__ __forceinline__ void gemm_phase(LAS unsigned char* lds, const Gemm g, const StaticOrder& S, const Epi& E, int wv) {
;     ...
;         if (!has_next) break;
; #pragma unroll
;         for (int a = 0; a < 2; ++a)
; #pragma unroll
;             for (int b = 0; b < 2; ++b)
; #pragma unroll
;                 for (int m = 0; m < 4; ++m)
; #pragma unroll
;                     for (int n = 0; n < 2; ++n) acc[a][b][m][n] = (f32x4){0.f, 0.f, 0.f, 0.f};
;         cur = nxt; cA = nA; cB = nB; ++ui;
;     }
;     PG8_WAIT_V(0);
;     if (wr == 0) PG8_BAR;
;     PG8_BAR;
;     __device__ __forceinline__ void operator()(const f32x4 (&acc)[2][2][4][2], const Unit& u, int wr, int wc, int fr, int fq) const {
;     ...
;         for (int ai = 0; ai < 2; ++ai)
; #pragma unroll
;             for (int m = 0; m < 4; ++m) {
;                 const size_t row = (size_t)u.pm * 256 + ai * 128 + wr * 64 + 4 * fr + m;
; #pragma unroll
;                 for (int bj = 0; bj < 2; ++bj)
; #pragma unroll
;                     for (int n = 0; n < 2; ++n) {
;                         const f32x4 v = gv[bj][n] * acc[ai][bj][m][n];
;                         u32x2 w; w.x = pk2(v[0], v[1]); w.y = pk2(v[2], v[3]);
;                         *(u32x2*)(O + row * D + u.pn * 256 + bj * 128 + wc * 32 + n * 16 + 4 * fq) = w;
;                     }
;             }
	v_cvt_pk_bf16_f32 v104, v104, v105
	v_cvt_pk_bf16_f32 v105, v106, v107
	v_cvt_pk_bf16_f32 v106, v100, v101
	v_cvt_pk_bf16_f32 v107, v102, v103
	v_pk_mul_f32 v[116:117], v[116:117], v[236:237]
	v_pk_mul_f32 v[118:119], v[118:119], v[238:239]
	v_pk_mul_f32 v[112:113], v[112:113], v[232:233]
	v_pk_mul_f32 v[114:115], v[114:115], v[234:235]
	v_permlane16_swap_b32_e32 v104, v106
	v_permlane16_swap_b32_e32 v105, v107
	global_store_dwordx4 v[162:163], v[104:107], off offset:256
	v_cvt_pk_bf16_f32 v116, v116, v117
	v_cvt_pk_bf16_f32 v117, v118, v119
	v_cvt_pk_bf16_f32 v118, v112, v113
	v_cvt_pk_bf16_f32 v119, v114, v115
	v_pk_mul_f32 v[92:93], v[92:93], v[228:229]
	v_pk_mul_f32 v[94:95], v[94:95], v[230:231]
	v_pk_mul_f32 v[88:89], v[88:89], v[224:225]
	v_pk_mul_f32 v[90:91], v[90:91], v[226:227]
	v_permlane16_swap_b32_e32 v116, v118
	v_permlane16_swap_b32_e32 v117, v119
	global_store_dwordx4 v[162:163], v[116:119], off offset:2048
	v_cvt_pk_bf16_f32 v92, v92, v93
	v_cvt_pk_bf16_f32 v93, v94, v95
	v_cvt_pk_bf16_f32 v94, v88, v89
	v_cvt_pk_bf16_f32 v95, v90, v91
	v_pk_mul_f32 v[108:109], v[108:109], v[236:237]
	v_pk_mul_f32 v[110:111], v[110:111], v[238:239]
	v_pk_mul_f32 v[96:97], v[96:97], v[232:233]
	v_pk_mul_f32 v[98:99], v[98:99], v[234:235]
	v_permlane16_swap_b32_e32 v92, v94
	v_permlane16_swap_b32_e32 v93, v95
	global_store_dwordx4 v[162:163], v[92:95], off offset:2304
	v_cvt_pk_bf16_f32 v108, v108, v109
	v_cvt_pk_bf16_f32 v109, v110, v111
	v_cvt_pk_bf16_f32 v110, v96, v97
	v_cvt_pk_bf16_f32 v111, v98, v99
	v_pk_mul_f32 v[84:85], v[84:85], v[228:229]
	v_pk_mul_f32 v[86:87], v[86:87], v[230:231]
	v_pk_mul_f32 v[76:77], v[76:77], v[224:225]
	v_pk_mul_f32 v[78:79], v[78:79], v[226:227]
	v_permlane16_swap_b32_e32 v108, v110
	v_permlane16_swap_b32_e32 v109, v111
	global_store_dwordx4 v[168:169], v[108:111], off
	v_cvt_pk_bf16_f32 v84, v84, v85
	v_cvt_pk_bf16_f32 v85, v86, v87
	v_cvt_pk_bf16_f32 v86, v76, v77
	v_cvt_pk_bf16_f32 v87, v78, v79
	v_pk_mul_f32 v[80:81], v[80:81], v[236:237]
	v_pk_mul_f32 v[82:83], v[82:83], v[238:239]
	v_pk_mul_f32 v[72:73], v[72:73], v[232:233]
	v_pk_mul_f32 v[74:75], v[74:75], v[234:235]
	v_permlane16_swap_b32_e32 v84, v86
	v_permlane16_swap_b32_e32 v85, v87
	global_store_dwordx4 v[168:169], v[84:87], off offset:256
	v_cvt_pk_bf16_f32 v80, v80, v81
	v_cvt_pk_bf16_f32 v81, v82, v83
	v_cvt_pk_bf16_f32 v82, v72, v73
	v_cvt_pk_bf16_f32 v83, v74, v75
	v_pk_mul_f32 v[68:69], v[68:69], v[228:229]
	v_pk_mul_f32 v[70:71], v[70:71], v[230:231]
	v_pk_mul_f32 v[64:65], v[64:65], v[224:225]
	v_pk_mul_f32 v[66:67], v[66:67], v[226:227]
	v_permlane16_swap_b32_e32 v80, v82
	v_permlane16_swap_b32_e32 v81, v83
	global_store_dwordx4 v[168:169], v[80:83], off offset:2048
	v_cvt_pk_bf16_f32 v68, v68, v69
	v_cvt_pk_bf16_f32 v69, v70, v71
	v_cvt_pk_bf16_f32 v70, v64, v65
	v_cvt_pk_bf16_f32 v71, v66, v67
	v_pk_mul_f32 v[60:61], v[60:61], v[236:237]
	v_pk_mul_f32 v[62:63], v[62:63], v[238:239]
	v_pk_mul_f32 v[56:57], v[56:57], v[232:233]
	v_pk_mul_f32 v[58:59], v[58:59], v[234:235]
	v_permlane16_swap_b32_e32 v68, v70
	v_permlane16_swap_b32_e32 v69, v71
	global_store_dwordx4 v[168:169], v[68:71], off offset:2304
	v_cvt_pk_bf16_f32 v60, v60, v61
	v_cvt_pk_bf16_f32 v61, v62, v63
	v_cvt_pk_bf16_f32 v62, v56, v57
	v_cvt_pk_bf16_f32 v63, v58, v59
	v_pk_mul_f32 v[52:53], v[52:53], v[228:229]
	v_pk_mul_f32 v[54:55], v[54:55], v[230:231]
	v_pk_mul_f32 v[44:45], v[44:45], v[224:225]
	v_pk_mul_f32 v[46:47], v[46:47], v[226:227]
	v_permlane16_swap_b32_e32 v60, v62
	v_permlane16_swap_b32_e32 v61, v63
	global_store_dwordx4 v[170:171], v[60:63], off
	v_cvt_pk_bf16_f32 v52, v52, v53
	v_cvt_pk_bf16_f32 v53, v54, v55
	v_cvt_pk_bf16_f32 v54, v44, v45
	v_cvt_pk_bf16_f32 v55, v46, v47
	v_pk_mul_f32 v[48:49], v[48:49], v[236:237]
	v_pk_mul_f32 v[50:51], v[50:51], v[238:239]
	v_pk_mul_f32 v[40:41], v[40:41], v[232:233]
	v_pk_mul_f32 v[42:43], v[42:43], v[234:235]
	v_permlane16_swap_b32_e32 v52, v54
	v_permlane16_swap_b32_e32 v53, v55
	global_store_dwordx4 v[170:171], v[52:55], off offset:256
	v_cvt_pk_bf16_f32 v48, v48, v49
	v_cvt_pk_bf16_f32 v49, v50, v51
	v_cvt_pk_bf16_f32 v50, v40, v41
	v_cvt_pk_bf16_f32 v51, v42, v43
	v_pk_mul_f32 v[36:37], v[36:37], v[228:229]
	v_pk_mul_f32 v[38:39], v[38:39], v[230:231]
	v_pk_mul_f32 v[28:29], v[28:29], v[224:225]
	v_pk_mul_f32 v[30:31], v[30:31], v[226:227]
	v_permlane16_swap_b32_e32 v48, v50
	v_permlane16_swap_b32_e32 v49, v51
	global_store_dwordx4 v[170:171], v[48:51], off offset:2048
	v_cvt_pk_bf16_f32 v36, v36, v37
	v_cvt_pk_bf16_f32 v37, v38, v39
	v_cvt_pk_bf16_f32 v38, v28, v29
	v_cvt_pk_bf16_f32 v39, v30, v31
	v_pk_mul_f32 v[32:33], v[32:33], v[236:237]
	v_pk_mul_f32 v[34:35], v[34:35], v[238:239]
	v_pk_mul_f32 v[24:25], v[24:25], v[232:233]
	v_pk_mul_f32 v[26:27], v[26:27], v[234:235]
	v_permlane16_swap_b32_e32 v36, v38
	v_permlane16_swap_b32_e32 v37, v39
	global_store_dwordx4 v[170:171], v[36:39], off offset:2304
	v_cvt_pk_bf16_f32 v32, v32, v33
	v_cvt_pk_bf16_f32 v33, v34, v35
	v_cvt_pk_bf16_f32 v34, v24, v25
	v_cvt_pk_bf16_f32 v35, v26, v27
	v_pk_mul_f32 v[20:21], v[20:21], v[228:229]
	v_pk_mul_f32 v[22:23], v[22:23], v[230:231]
	v_pk_mul_f32 v[12:13], v[12:13], v[224:225]
	v_pk_mul_f32 v[14:15], v[14:15], v[226:227]
	v_permlane16_swap_b32_e32 v32, v34
	v_permlane16_swap_b32_e32 v33, v35
	global_store_dwordx4 v[222:223], v[32:35], off
	v_cvt_pk_bf16_f32 v20, v20, v21
	v_cvt_pk_bf16_f32 v21, v22, v23
	v_cvt_pk_bf16_f32 v22, v12, v13
	v_cvt_pk_bf16_f32 v23, v14, v15
	v_pk_mul_f32 v[16:17], v[16:17], v[236:237]
	v_pk_mul_f32 v[18:19], v[18:19], v[238:239]
	v_pk_mul_f32 v[8:9], v[8:9], v[232:233]
	v_pk_mul_f32 v[10:11], v[10:11], v[234:235]
	v_permlane16_swap_b32_e32 v20, v22
	v_permlane16_swap_b32_e32 v21, v23
	global_store_dwordx4 v[222:223], v[20:23], off offset:256
	v_cvt_pk_bf16_f32 v16, v16, v17
	v_cvt_pk_bf16_f32 v17, v18, v19
	v_cvt_pk_bf16_f32 v18, v8, v9
	v_cvt_pk_bf16_f32 v19, v10, v11
	v_pk_mul_f32 v[4:5], v[4:5], v[228:229]
	v_pk_mul_f32 v[6:7], v[6:7], v[230:231]
	v_pk_mul_f32 v[0:1], v[0:1], v[224:225]
	v_pk_mul_f32 v[2:3], v[2:3], v[226:227]
	v_permlane16_swap_b32_e32 v16, v18
	v_permlane16_swap_b32_e32 v17, v19
	global_store_dwordx4 v[222:223], v[16:19], off offset:2048
	v_cvt_pk_bf16_f32 v4, v4, v5
	v_cvt_pk_bf16_f32 v5, v6, v7
	v_cvt_pk_bf16_f32 v6, v0, v1
	v_cvt_pk_bf16_f32 v7, v2, v3
	s_nop 1
	v_permlane16_swap_b32_e32 v4, v6
	v_permlane16_swap_b32_e32 v5, v7
	global_store_dwordx4 v[222:223], v[4:7], off offset:2304
	s_and_b64 vcc, exec, s[4:5]
	s_cbranch_vccz .LBB0_839
	s_waitcnt vmcnt(0)
	s_cmpk_gt_u32 s52, 0xff
	s_cbranch_scc1 .LBB0_850
	s_barrier

; #define PG8_STAGE(bufoff, gbase, voff) do { _Pragma("unroll") for (int _i = 0; _i < 2; ++_i) \
;         __builtin_amdgcn_global_load_lds((const unsigned*)((const char*)(gbase) + (voff)[_i]), (LAS unsigned*)(lds + (bufoff) + ldsw + _i * 8192), 16, 0, 0); } while (0)
; #define PG8_LDA(dst, b, h) do { _Pragma("unroll") for (int m = 0; m < 4; ++m) _Pragma("unroll") for (int k = 0; k < 2; ++k) dst[m][k] = *(const LAS bf16x8*)(lds + PG8_SA(b, h) + aoff + m * 2048 + k * 1024); } while (0)
; #define PG8_LDB(dst, b, h) do { _Pragma("unroll") for (int n = 0; n < 2; ++n) _Pragma("unroll") for (int k = 0; k < 2; ++k) dst[n][k] = *(const LAS bf16x8*)(lds + PG8_SB(b, h) + boff + n * 2048 + k * 1024); } while (0)
; #define PG8_MMA(ai, bj, At, Bt) do { __builtin_amdgcn_s_setprio(1); _Pragma("unroll") for (int m = 0; m < 4; ++m) _Pragma("unroll") for (int n = 0; n < 2; ++n) _Pragma("unroll") for (int k = 0; k < 2; ++k) \
;         acc[ai][bj][m][n] = __builtin_amdgcn_mfma_f32_16x16x32_bf16(Bt[n][k], At[m][k], acc[ai][bj][m][n], 0, 0, 0); __builtin_amdgcn_s_setprio(0); } while (0)
; #define PG8_WAIT_V(n) asm volatile("s_waitcnt vmcnt(" #n ")" ::: "memory")
; #define PG8_WAIT_L(n) asm volatile("s_waitcnt lgkmcnt(" #n ")" ::: "memory")
; template <class Epi>
; __device__ __forceinline__ void gemm_phase(LAS unsigned char* lds, const Gemm g, const StaticOrder& S, const Epi& E, int wv) {
;     ...
;         for (int t = 0; t < nt; t += 2) {
;             const bool last = (t == nt - 2);
;             const char* a1 = cA + (size_t)(t + 1) * kstep;
;             const char* a2 = last ? nA : cA + (size_t)(t + 2) * kstep; const char* b2 = last ? nB : cB + (size_t)(t + 2) * kstep;
;             const char* a3 = a2 + kstep; const char* b3 = b2 + kstep;
;             PG8_LDB(B0, 0, 0); PG8_SCHED; PG8_LDA(At, 0, 0); PG8_STAGE(PG8_SA(1, 1), a1 + hstep, voffA);
;             PG8_WAIT_L(8); PG8_BAR; PG8_WAIT_L(0); PG8_MMA(0, 0, At, B0); PG8_BAR; PG8_SCHED;
;             PG8_LDB(B1, 0, 1); PG8_STAGE(PG8_SB(0, 0), b2, voffB);
;             PG8_BAR; PG8_WAIT_L(0); PG8_MMA(0, 1, At, B1); PG8_BAR;
;             PG8_LDA(At, 0, 1); PG8_STAGE(PG8_SA(0, 0), a2, voffA);
;             PG8_BAR; PG8_WAIT_L(0); PG8_MMA(1, 0, At, B0); PG8_BAR; PG8_SCHED;
;             PG8_STAGE(PG8_SB(0, 1), b2 + hstep, voffB);
;             PG8_WAIT_V(6); PG8_BAR; PG8_MMA(1, 1, At, B1); PG8_BAR;
.LBB0_999:
	s_barrier
	ds_read_b128 v[128:131], v214
	ds_read_b128 v[132:135], v214 offset:1024
	ds_read_b128 v[136:139], v214 offset:2048
	ds_read_b128 v[140:143], v214 offset:3072
	s_add_u32 s6, s12, 0x100
	s_addc_u32 s7, s13, 0
	s_cmp_eq_u32 s49, 12
	s_cselect_b32 s17, s43, s7
	s_cselect_b32 s16, s42, s6
	s_cselect_b32 s15, s9, s48
	s_cselect_b32 s14, s41, s46
	ds_read_b128 v[144:147], v215
	ds_read_b128 v[148:151], v215 offset:1024
	ds_read_b128 v[152:155], v215 offset:2048
	ds_read_b128 v[156:159], v215 offset:3072
	ds_read_b128 v[178:181], v215 offset:4096
	ds_read_b128 v[182:185], v215 offset:5120
	ds_read_b128 v[186:189], v215 offset:6144
	ds_read_b128 v[190:193], v215 offset:7168
	ds_read_b128 v[194:197], v216
	ds_read_b128 v[198:201], v216 offset:1024
	ds_read_b128 v[202:205], v216 offset:2048
	ds_read_b128 v[206:209], v216 offset:3072
	v_lshl_add_u64 v[252:253], s[12:13], 0, v[170:171]
	s_add_i32 m0, s68, 0xc000
	s_nop 0
	global_load_lds_dwordx4 v[252:253], off
	v_lshl_add_u64 v[252:253], s[12:13], 0, v[172:173]
	s_add_i32 m0, s68, 0xe000
	s_nop 0
	global_load_lds_dwordx4 v[252:253], off
	s_waitcnt vmcnt(8)
	s_waitcnt lgkmcnt(0)
	s_barrier
	s_setprio 1
	v_mfma_f32_16x16x32_bf16 v[124:127], v[128:131], v[144:147], v[124:127]
	v_mfma_f32_16x16x32_bf16 v[60:63], v[136:139], v[144:147], v[60:63]
	v_mfma_f32_16x16x32_bf16 v[116:119], v[128:131], v[152:155], v[116:119]
	v_mfma_f32_16x16x32_bf16 v[52:55], v[136:139], v[152:155], v[52:55]
	v_mfma_f32_16x16x32_bf16 v[112:115], v[128:131], v[178:181], v[112:115]
	v_mfma_f32_16x16x32_bf16 v[48:51], v[136:139], v[178:181], v[48:51]
	v_mfma_f32_16x16x32_bf16 v[108:111], v[128:131], v[186:189], v[108:111]
	v_mfma_f32_16x16x32_bf16 v[44:47], v[136:139], v[186:189], v[44:47]
	v_mfma_f32_16x16x32_bf16 v[124:127], v[132:135], v[148:151], v[124:127]
	v_mfma_f32_16x16x32_bf16 v[60:63], v[140:143], v[148:151], v[60:63]
	v_mfma_f32_16x16x32_bf16 v[116:119], v[132:135], v[156:159], v[116:119]
	v_mfma_f32_16x16x32_bf16 v[52:55], v[140:143], v[156:159], v[52:55]
	v_mfma_f32_16x16x32_bf16 v[112:115], v[132:135], v[182:185], v[112:115]
	v_mfma_f32_16x16x32_bf16 v[48:51], v[140:143], v[182:185], v[48:51]
	v_mfma_f32_16x16x32_bf16 v[108:111], v[132:135], v[190:193], v[108:111]
	v_mfma_f32_16x16x32_bf16 v[44:47], v[140:143], v[190:193], v[44:47]
	v_mfma_f32_16x16x32_bf16 v[120:123], v[194:197], v[144:147], v[120:123]
	v_mfma_f32_16x16x32_bf16 v[56:59], v[202:205], v[144:147], v[56:59]
	v_mfma_f32_16x16x32_bf16 v[104:107], v[194:197], v[152:155], v[104:107]
	v_mfma_f32_16x16x32_bf16 v[40:43], v[202:205], v[152:155], v[40:43]
	v_mfma_f32_16x16x32_bf16 v[100:103], v[194:197], v[178:181], v[100:103]
	v_mfma_f32_16x16x32_bf16 v[36:39], v[202:205], v[178:181], v[36:39]
	v_mfma_f32_16x16x32_bf16 v[96:99], v[194:197], v[186:189], v[96:99]
	v_mfma_f32_16x16x32_bf16 v[32:35], v[202:205], v[186:189], v[32:35]
	v_mfma_f32_16x16x32_bf16 v[120:123], v[198:201], v[148:151], v[120:123]
	v_mfma_f32_16x16x32_bf16 v[56:59], v[206:209], v[148:151], v[56:59]
	v_mfma_f32_16x16x32_bf16 v[104:107], v[198:201], v[156:159], v[104:107]
	v_mfma_f32_16x16x32_bf16 v[40:43], v[206:209], v[156:159], v[40:43]
	v_mfma_f32_16x16x32_bf16 v[100:103], v[198:201], v[182:185], v[100:103]
	v_mfma_f32_16x16x32_bf16 v[36:39], v[206:209], v[182:185], v[36:39]
	v_mfma_f32_16x16x32_bf16 v[96:99], v[198:201], v[190:193], v[96:99]
	v_mfma_f32_16x16x32_bf16 v[32:35], v[206:209], v[190:193], v[32:35]
	s_setprio 0
	s_barrier
	ds_read_b128 v[144:147], v215 offset:16384
	ds_read_b128 v[148:151], v215 offset:17408
	ds_read_b128 v[152:155], v215 offset:18432
	ds_read_b128 v[156:159], v215 offset:19456
	ds_read_b128 v[178:181], v215 offset:20480
	ds_read_b128 v[182:185], v215 offset:21504
	ds_read_b128 v[186:189], v215 offset:22528
	ds_read_b128 v[190:193], v215 offset:23552
	s_add_i32 s12, s90, s67
	v_lshl_add_u64 v[210:211], s[14:15], 0, v[162:163]
	s_mov_b32 m0, s12
	s_nop 0
	global_load_lds_dwordx4 v[210:211], off
	v_lshl_add_u64 v[220:221], s[14:15], 0, v[166:167]
	s_add_i32 m0, s12, 0x2000
	s_nop 0
	global_load_lds_dwordx4 v[220:221], off
	s_mov_b32 m0, s68
	v_lshl_add_u64 v[222:223], s[16:17], 0, v[160:161]
	global_load_lds_dwordx4 v[222:223], off
	v_lshl_add_u64 v[224:225], s[16:17], 0, v[164:165]
	s_mov_b32 m0, s69
	s_nop 0
	global_load_lds_dwordx4 v[224:225], off
	s_add_u32 s12, s14, 0x40000
	s_addc_u32 s13, s15, 0
	s_add_i32 s50, s91, s67
	v_lshl_add_u64 v[254:255], s[12:13], 0, v[162:163]
	s_mov_b32 m0, s50
	s_nop 0
	global_load_lds_dwordx4 v[254:255], off
	v_lshl_add_u64 v[254:255], s[12:13], 0, v[166:167]
	s_add_i32 m0, s50, 0x2000
	s_nop 0
	global_load_lds_dwordx4 v[254:255], off
	s_waitcnt vmcnt(8)
	s_waitcnt lgkmcnt(0)
	s_barrier
; #define PG8_STAGE(bufoff, gbase, voff) do { _Pragma("unroll") for (int _i = 0; _i < 2; ++_i) \
;         __builtin_amdgcn_global_load_lds((const unsigned*)((const char*)(gbase) + (voff)[_i]), (LAS unsigned*)(lds + (bufoff) + ldsw + _i * 8192), 16, 0, 0); } while (0)
; #define PG8_LDA(dst, b, h) do { _Pragma("unroll") for (int m = 0; m < 4; ++m) _Pragma("unroll") for (int k = 0; k < 2; ++k) dst[m][k] = *(const LAS bf16x8*)(lds + PG8_SA(b, h) + aoff + m * 2048 + k * 1024); } while (0)
; #define PG8_LDB(dst, b, h) do { _Pragma("unroll") for (int n = 0; n < 2; ++n) _Pragma("unroll") for (int k = 0; k < 2; ++k) dst[n][k] = *(const LAS bf16x8*)(lds + PG8_SB(b, h) + boff + n * 2048 + k * 1024); } while (0)
; #define PG8_MMA(ai, bj, At, Bt) do { __builtin_amdgcn_s_setprio(1); _Pragma("unroll") for (int m = 0; m < 4; ++m) _Pragma("unroll") for (int n = 0; n < 2; ++n) _Pragma("unroll") for (int k = 0; k < 2; ++k) \
;         acc[ai][bj][m][n] = __builtin_amdgcn_mfma_f32_16x16x32_bf16(Bt[n][k], At[m][k], acc[ai][bj][m][n], 0, 0, 0); __builtin_amdgcn_s_setprio(0); } while (0)
; #define PG8_WAIT_V(n) asm volatile("s_waitcnt vmcnt(" #n ")" ::: "memory")
; #define PG8_WAIT_L(n) asm volatile("s_waitcnt lgkmcnt(" #n ")" ::: "memory")
; #define PG8_BAR __builtin_amdgcn_s_barrier()
; #define PG8_SCHED __builtin_amdgcn_sched_barrier(0)
; template <class Epi>
; __device__ __forceinline__ void gemm_phase(LAS unsigned char* lds, const Gemm g, const StaticOrder& S, const Epi& E, int wv) {
;     ...
;             PG8_BAR; PG8_WAIT_L(0); PG8_MMA(0, 1, At, B1); PG8_BAR;
;             PG8_LDA(At, 0, 1); PG8_STAGE(PG8_SA(0, 0), a2, voffA);
;             PG8_BAR; PG8_WAIT_L(0); PG8_MMA(1, 0, At, B0); PG8_BAR; PG8_SCHED;
;             PG8_STAGE(PG8_SB(0, 1), b2 + hstep, voffB);
;             PG8_WAIT_V(6); PG8_BAR; PG8_MMA(1, 1, At, B1); PG8_BAR;
;             PG8_LDB(B0, 1, 0); PG8_SCHED; PG8_LDA(At, 1, 0); PG8_STAGE(PG8_SA(0, 1), a2 + hstep, voffA);
;             PG8_WAIT_L(8); PG8_BAR; PG8_WAIT_L(0); PG8_MMA(0, 0, At, B0); PG8_BAR; PG8_SCHED;
;             PG8_LDB(B1, 1, 1); PG8_STAGE(PG8_SB(1, 0), b3, voffB);
;             PG8_BAR; PG8_WAIT_L(0); PG8_MMA(0, 1, At, B1); PG8_BAR;
	s_setprio 1
	v_mfma_f32_16x16x32_bf16 v[92:95], v[128:131], v[144:147], v[92:95]
	v_mfma_f32_16x16x32_bf16 v[28:31], v[136:139], v[144:147], v[28:31]
	v_mfma_f32_16x16x32_bf16 v[84:87], v[128:131], v[152:155], v[84:87]
	v_mfma_f32_16x16x32_bf16 v[20:23], v[136:139], v[152:155], v[20:23]
	v_mfma_f32_16x16x32_bf16 v[80:83], v[128:131], v[178:181], v[80:83]
	v_mfma_f32_16x16x32_bf16 v[16:19], v[136:139], v[178:181], v[16:19]
	v_mfma_f32_16x16x32_bf16 v[76:79], v[128:131], v[186:189], v[76:79]
	v_mfma_f32_16x16x32_bf16 v[12:15], v[136:139], v[186:189], v[12:15]
	v_mfma_f32_16x16x32_bf16 v[92:95], v[132:135], v[148:151], v[92:95]
	v_mfma_f32_16x16x32_bf16 v[28:31], v[140:143], v[148:151], v[28:31]
	v_mfma_f32_16x16x32_bf16 v[84:87], v[132:135], v[156:159], v[84:87]
	v_mfma_f32_16x16x32_bf16 v[20:23], v[140:143], v[156:159], v[20:23]
	v_mfma_f32_16x16x32_bf16 v[80:83], v[132:135], v[182:185], v[80:83]
	v_mfma_f32_16x16x32_bf16 v[16:19], v[140:143], v[182:185], v[16:19]
	v_mfma_f32_16x16x32_bf16 v[76:79], v[132:135], v[190:193], v[76:79]
	v_mfma_f32_16x16x32_bf16 v[12:15], v[140:143], v[190:193], v[12:15]
	v_mfma_f32_16x16x32_bf16 v[88:91], v[194:197], v[144:147], v[88:91]
	v_mfma_f32_16x16x32_bf16 v[24:27], v[202:205], v[144:147], v[24:27]
	v_mfma_f32_16x16x32_bf16 v[72:75], v[194:197], v[152:155], v[72:75]
	v_mfma_f32_16x16x32_bf16 v[8:11], v[202:205], v[152:155], v[8:11]
	v_mfma_f32_16x16x32_bf16 v[68:71], v[194:197], v[178:181], v[68:71]
	v_mfma_f32_16x16x32_bf16 v[4:7], v[202:205], v[178:181], v[4:7]
	v_mfma_f32_16x16x32_bf16 v[64:67], v[194:197], v[186:189], v[64:67]
	v_mfma_f32_16x16x32_bf16 v[0:3], v[202:205], v[186:189], v[0:3]
	v_mfma_f32_16x16x32_bf16 v[88:91], v[198:201], v[148:151], v[88:91]
	v_mfma_f32_16x16x32_bf16 v[24:27], v[206:209], v[148:151], v[24:27]
	v_mfma_f32_16x16x32_bf16 v[72:75], v[198:201], v[156:159], v[72:75]
	v_mfma_f32_16x16x32_bf16 v[8:11], v[206:209], v[156:159], v[8:11]
	v_mfma_f32_16x16x32_bf16 v[68:71], v[198:201], v[182:185], v[68:71]
	v_mfma_f32_16x16x32_bf16 v[4:7], v[206:209], v[182:185], v[4:7]
	v_mfma_f32_16x16x32_bf16 v[64:67], v[198:201], v[190:193], v[64:67]
	v_mfma_f32_16x16x32_bf16 v[0:3], v[206:209], v[190:193], v[0:3]
	s_setprio 0
	s_add_i32 s50, 0, 0x18000
	v_add_u32_e32 v140, s50, v213
	s_barrier
	ds_read_b128 v[128:131], v140
	ds_read_b128 v[132:135], v140 offset:1024
	ds_read_b128 v[136:139], v140 offset:2048
	ds_read_b128 v[140:143], v140 offset:3072
	s_add_u32 s12, s16, 0x40000
	s_addc_u32 s13, s17, 0
	ds_read_b128 v[144:147], v215 offset:32768
	ds_read_b128 v[148:151], v215 offset:33792
	ds_read_b128 v[152:155], v215 offset:34816
	ds_read_b128 v[156:159], v215 offset:35840
	ds_read_b128 v[178:181], v215 offset:36864
	ds_read_b128 v[182:185], v215 offset:37888
	ds_read_b128 v[186:189], v215 offset:38912
	ds_read_b128 v[190:193], v215 offset:39936
	s_mov_b32 m0, s70
	v_lshl_add_u64 v[252:253], s[12:13], 0, v[160:161]
	global_load_lds_dwordx4 v[252:253], off
	v_lshl_add_u64 v[252:253], s[12:13], 0, v[164:165]
	s_mov_b32 m0, s71
	s_nop 0
	global_load_lds_dwordx4 v[252:253], off
	s_add_i32 s16, 0, 0x1c000
	v_add_u32_e32 v168, s16, v213
	ds_read_b128 v[194:197], v168
	ds_read_b128 v[198:201], v168 offset:1024
	ds_read_b128 v[202:205], v168 offset:2048
	ds_read_b128 v[206:209], v168 offset:3072
	s_waitcnt vmcnt(8)
	s_waitcnt lgkmcnt(0)
	s_barrier
	s_setprio 1
	v_mfma_f32_16x16x32_bf16 v[124:127], v[128:131], v[144:147], v[124:127]
	v_mfma_f32_16x16x32_bf16 v[60:63], v[136:139], v[144:147], v[60:63]
	v_mfma_f32_16x16x32_bf16 v[116:119], v[128:131], v[152:155], v[116:119]
	v_mfma_f32_16x16x32_bf16 v[52:55], v[136:139], v[152:155], v[52:55]
	v_mfma_f32_16x16x32_bf16 v[112:115], v[128:131], v[178:181], v[112:115]
	v_mfma_f32_16x16x32_bf16 v[48:51], v[136:139], v[178:181], v[48:51]
	v_mfma_f32_16x16x32_bf16 v[108:111], v[128:131], v[186:189], v[108:111]
	v_mfma_f32_16x16x32_bf16 v[44:47], v[136:139], v[186:189], v[44:47]
	v_mfma_f32_16x16x32_bf16 v[124:127], v[132:135], v[148:151], v[124:127]
	v_mfma_f32_16x16x32_bf16 v[60:63], v[140:143], v[148:151], v[60:63]
	v_mfma_f32_16x16x32_bf16 v[116:119], v[132:135], v[156:159], v[116:119]
	v_mfma_f32_16x16x32_bf16 v[52:55], v[140:143], v[156:159], v[52:55]
	v_mfma_f32_16x16x32_bf16 v[112:115], v[132:135], v[182:185], v[112:115]
	v_mfma_f32_16x16x32_bf16 v[48:51], v[140:143], v[182:185], v[48:51]
	v_mfma_f32_16x16x32_bf16 v[108:111], v[132:135], v[190:193], v[108:111]
	v_mfma_f32_16x16x32_bf16 v[44:47], v[140:143], v[190:193], v[44:47]
	v_mfma_f32_16x16x32_bf16 v[120:123], v[194:197], v[144:147], v[120:123]
	v_mfma_f32_16x16x32_bf16 v[56:59], v[202:205], v[144:147], v[56:59]
	v_mfma_f32_16x16x32_bf16 v[104:107], v[194:197], v[152:155], v[104:107]
	v_mfma_f32_16x16x32_bf16 v[40:43], v[202:205], v[152:155], v[40:43]
	v_mfma_f32_16x16x32_bf16 v[100:103], v[194:197], v[178:181], v[100:103]
	v_mfma_f32_16x16x32_bf16 v[36:39], v[202:205], v[178:181], v[36:39]
	v_mfma_f32_16x16x32_bf16 v[96:99], v[194:197], v[186:189], v[96:99]
	v_mfma_f32_16x16x32_bf16 v[32:35], v[202:205], v[186:189], v[32:35]
	v_mfma_f32_16x16x32_bf16 v[120:123], v[198:201], v[148:151], v[120:123]
	v_mfma_f32_16x16x32_bf16 v[56:59], v[206:209], v[148:151], v[56:59]
	v_mfma_f32_16x16x32_bf16 v[104:107], v[198:201], v[156:159], v[104:107]
	v_mfma_f32_16x16x32_bf16 v[40:43], v[206:209], v[156:159], v[40:43]
	v_mfma_f32_16x16x32_bf16 v[100:103], v[198:201], v[182:185], v[100:103]
	v_mfma_f32_16x16x32_bf16 v[36:39], v[206:209], v[182:185], v[36:39]
	v_mfma_f32_16x16x32_bf16 v[96:99], v[198:201], v[190:193], v[96:99]
	v_mfma_f32_16x16x32_bf16 v[32:35], v[206:209], v[190:193], v[32:35]
	s_setprio 0
	s_barrier
; __device__ __forceinline__ int lane_fresh() { unsigned m = ~0u; asm volatile("" : "+s"(m)); return (int)__builtin_amdgcn_mbcnt_hi(m, __builtin_amdgcn_mbcnt_lo(m, 0u)); }
; #define PG8_STAGE(bufoff, gbase, voff) do { _Pragma("unroll") for (int _i = 0; _i < 2; ++_i) \
;         __builtin_amdgcn_global_load_lds((const unsigned*)((const char*)(gbase) + (voff)[_i]), (LAS unsigned*)(lds + (bufoff) + ldsw + _i * 8192), 16, 0, 0); } while (0)
; #define PG8_LDA(dst, b, h) do { _Pragma("unroll") for (int m = 0; m < 4; ++m) _Pragma("unroll") for (int k = 0; k < 2; ++k) dst[m][k] = *(const LAS bf16x8*)(lds + PG8_SA(b, h) + aoff + m * 2048 + k * 1024); } while (0)
; #define PG8_LDB(dst, b, h) do { _Pragma("unroll") for (int n = 0; n < 2; ++n) _Pragma("unroll") for (int k = 0; k < 2; ++k) dst[n][k] = *(const LAS bf16x8*)(lds + PG8_SB(b, h) + boff + n * 2048 + k * 1024); } while (0)
; #define PG8_MMA(ai, bj, At, Bt) do { __builtin_amdgcn_s_setprio(1); _Pragma("unroll") for (int m = 0; m < 4; ++m) _Pragma("unroll") for (int n = 0; n < 2; ++n) _Pragma("unroll") for (int k = 0; k < 2; ++k) \
;         acc[ai][bj][m][n] = __builtin_amdgcn_mfma_f32_16x16x32_bf16(Bt[n][k], At[m][k], acc[ai][bj][m][n], 0, 0, 0); __builtin_amdgcn_s_setprio(0); } while (0)
; #define PG8_WAIT_V(n) asm volatile("s_waitcnt vmcnt(" #n ")" ::: "memory")
; #define PG8_WAIT_L(n) asm volatile("s_waitcnt lgkmcnt(" #n ")" ::: "memory")
; #define PG8_BAR __builtin_amdgcn_s_barrier()
; template <class Epi>
; __device__ __forceinline__ void gemm_phase(LAS unsigned char* lds, const Gemm g, const StaticOrder& S, const Epi& E, int wv) {
;     ...
;             PG8_LDB(B1, 1, 1); PG8_STAGE(PG8_SB(1, 0), b3, voffB);
;             PG8_BAR; PG8_WAIT_L(0); PG8_MMA(0, 1, At, B1); PG8_BAR;
;             PG8_LDA(At, 1, 1); PG8_STAGE(PG8_SA(1, 0), a3, voffA);
;             PG8_BAR; PG8_WAIT_L(0); PG8_MMA(1, 0, At, B0); PG8_BAR; PG8_SCHED;
;             PG8_STAGE(PG8_SB(1, 1), b3 + hstep, voffB);
;             PG8_WAIT_V(6); PG8_BAR; PG8_MMA(1, 1, At, B1); PG8_BAR;
;         }
;         { const int ln2 = lane_fresh();
;           E(acc, cur, wr, wc, ln2 & 15, ln2 >> 4); }
;     __device__ __forceinline__ void operator()(const f32x4 (&acc)[2][2][4][2], const Unit& u, int wr, int wc, int fr, int fq) const {
;         if (wr == 0) { __builtin_amdgcn_s_barrier(); } asm volatile("" ::: "memory");
	ds_read_b128 v[144:147], v215 offset:49152
	ds_read_b128 v[148:151], v215 offset:50176
	ds_read_b128 v[152:155], v215 offset:51200
	ds_read_b128 v[156:159], v215 offset:52224
	ds_read_b128 v[178:181], v215 offset:53248
	ds_read_b128 v[182:185], v215 offset:54272
	ds_read_b128 v[186:189], v215 offset:55296
	ds_read_b128 v[190:193], v215 offset:56320
	s_add_i32 s12, s50, s67
	v_lshl_add_u64 v[210:211], v[210:211], 0, s[30:31]
	s_mov_b32 m0, s12
	s_nop 0
	global_load_lds_dwordx4 v[210:211], off
	v_lshl_add_u64 v[210:211], v[220:221], 0, s[30:31]
	s_add_i32 m0, s12, 0x2000
	s_nop 0
	global_load_lds_dwordx4 v[210:211], off
	s_mov_b32 m0, s77
	v_lshl_add_u64 v[210:211], v[222:223], 0, s[30:31]
	global_load_lds_dwordx4 v[210:211], off
	v_lshl_add_u64 v[210:211], v[224:225], 0, s[30:31]
	s_mov_b32 m0, s78
	s_nop 0
	global_load_lds_dwordx4 v[210:211], off
	s_add_u32 s12, s14, 0x40080
	s_addc_u32 s13, s15, 0
	s_add_i32 s14, s16, s67
	v_lshl_add_u64 v[254:255], s[12:13], 0, v[162:163]
	s_mov_b32 m0, s14
	s_nop 0
	global_load_lds_dwordx4 v[254:255], off
	v_lshl_add_u64 v[254:255], s[12:13], 0, v[166:167]
	s_add_i32 m0, s14, 0x2000
	s_nop 0
	global_load_lds_dwordx4 v[254:255], off
	s_waitcnt vmcnt(8)
	s_waitcnt lgkmcnt(0)
	s_barrier
	s_setprio 1
	v_mfma_f32_16x16x32_bf16 v[92:95], v[128:131], v[144:147], v[92:95]
	v_mfma_f32_16x16x32_bf16 v[28:31], v[136:139], v[144:147], v[28:31]
	v_mfma_f32_16x16x32_bf16 v[84:87], v[128:131], v[152:155], v[84:87]
	v_mfma_f32_16x16x32_bf16 v[20:23], v[136:139], v[152:155], v[20:23]
	v_mfma_f32_16x16x32_bf16 v[80:83], v[128:131], v[178:181], v[80:83]
	v_mfma_f32_16x16x32_bf16 v[16:19], v[136:139], v[178:181], v[16:19]
	v_mfma_f32_16x16x32_bf16 v[76:79], v[128:131], v[186:189], v[76:79]
	v_mfma_f32_16x16x32_bf16 v[12:15], v[136:139], v[186:189], v[12:15]
	v_mfma_f32_16x16x32_bf16 v[92:95], v[132:135], v[148:151], v[92:95]
	v_mfma_f32_16x16x32_bf16 v[28:31], v[140:143], v[148:151], v[28:31]
	v_mfma_f32_16x16x32_bf16 v[84:87], v[132:135], v[156:159], v[84:87]
	v_mfma_f32_16x16x32_bf16 v[20:23], v[140:143], v[156:159], v[20:23]
	v_mfma_f32_16x16x32_bf16 v[80:83], v[132:135], v[182:185], v[80:83]
	v_mfma_f32_16x16x32_bf16 v[16:19], v[140:143], v[182:185], v[16:19]
	v_mfma_f32_16x16x32_bf16 v[76:79], v[132:135], v[190:193], v[76:79]
	v_mfma_f32_16x16x32_bf16 v[12:15], v[140:143], v[190:193], v[12:15]
	v_mfma_f32_16x16x32_bf16 v[88:91], v[194:197], v[144:147], v[88:91]
	v_mfma_f32_16x16x32_bf16 v[24:27], v[202:205], v[144:147], v[24:27]
	v_mfma_f32_16x16x32_bf16 v[72:75], v[194:197], v[152:155], v[72:75]
	v_mfma_f32_16x16x32_bf16 v[8:11], v[202:205], v[152:155], v[8:11]
	v_mfma_f32_16x16x32_bf16 v[68:71], v[194:197], v[178:181], v[68:71]
	v_mfma_f32_16x16x32_bf16 v[4:7], v[202:205], v[178:181], v[4:7]
	v_mfma_f32_16x16x32_bf16 v[64:67], v[194:197], v[186:189], v[64:67]
	v_mfma_f32_16x16x32_bf16 v[0:3], v[202:205], v[186:189], v[0:3]
	v_mfma_f32_16x16x32_bf16 v[88:91], v[198:201], v[148:151], v[88:91]
	v_mfma_f32_16x16x32_bf16 v[24:27], v[206:209], v[148:151], v[24:27]
	v_mfma_f32_16x16x32_bf16 v[72:75], v[198:201], v[156:159], v[72:75]
	v_mfma_f32_16x16x32_bf16 v[8:11], v[206:209], v[156:159], v[8:11]
	v_mfma_f32_16x16x32_bf16 v[68:71], v[198:201], v[182:185], v[68:71]
	v_mfma_f32_16x16x32_bf16 v[4:7], v[206:209], v[182:185], v[4:7]
	v_mfma_f32_16x16x32_bf16 v[64:67], v[198:201], v[190:193], v[64:67]
	v_mfma_f32_16x16x32_bf16 v[0:3], v[206:209], v[190:193], v[0:3]
	s_setprio 0
	s_add_i32 s49, s49, 2
	s_add_u32 s46, s46, 0x100
	s_addc_u32 s48, s48, 0
	s_cmp_gt_u32 s49, 13
	s_mov_b64 s[12:13], s[6:7]
	s_cbranch_scc0 .LBB0_999
	s_barrier
	v_cndmask_b32_e64 v128, 0, 1, s[34:35]
	s_mov_b32 s9, -1
	v_cmp_ne_u32_e64 s[6:7], 1, v128
	s_andn2_b64 vcc, exec, s[34:35]
	s_cbranch_vccnz .LBB0_1002
	s_barrier

; #define PG8_STAGE(bufoff, gbase, voff) do { _Pragma("unroll") for (int _i = 0; _i < 2; ++_i) \
;         __builtin_amdgcn_global_load_lds((const unsigned*)((const char*)(gbase) + (voff)[_i]), (LAS unsigned*)(lds + (bufoff) + ldsw + _i * 8192), 16, 0, 0); } while (0)
; #define PG8_LDA(dst, b, h) do { _Pragma("unroll") for (int m = 0; m < 4; ++m) _Pragma("unroll") for (int k = 0; k < 2; ++k) dst[m][k] = *(const LAS bf16x8*)(lds + PG8_SA(b, h) + aoff + m * 2048 + k * 1024); } while (0)
; #define PG8_LDB(dst, b, h) do { _Pragma("unroll") for (int n = 0; n < 2; ++n) _Pragma("unroll") for (int k = 0; k < 2; ++k) dst[n][k] = *(const LAS bf16x8*)(lds + PG8_SB(b, h) + boff + n * 2048 + k * 1024); } while (0)
; #define PG8_MMA(ai, bj, At, Bt) do { __builtin_amdgcn_s_setprio(1); _Pragma("unroll") for (int m = 0; m < 4; ++m) _Pragma("unroll") for (int n = 0; n < 2; ++n) _Pragma("unroll") for (int k = 0; k < 2; ++k) \
;         acc[ai][bj][m][n] = __builtin_amdgcn_mfma_f32_16x16x32_bf16(Bt[n][k], At[m][k], acc[ai][bj][m][n], 0, 0, 0); __builtin_amdgcn_s_setprio(0); } while (0)
; #define PG8_WAIT_V(n) asm volatile("s_waitcnt vmcnt(" #n ")" ::: "memory")
; #define PG8_WAIT_L(n) asm volatile("s_waitcnt lgkmcnt(" #n ")" ::: "memory")
; template <class Epi>
; __device__ __forceinline__ void gemm_phase(LAS unsigned char* lds, const Gemm g, const StaticOrder& S, const Epi& E, int wv) {
;     ...
;         for (int t = 0; t < nt; t += 2) {
;             const bool last = (t == nt - 2);
;             const char* a1 = cA + (size_t)(t + 1) * kstep;
;             const char* a2 = last ? nA : cA + (size_t)(t + 2) * kstep; const char* b2 = last ? nB : cB + (size_t)(t + 2) * kstep;
;             const char* a3 = a2 + kstep; const char* b3 = b2 + kstep;
;             PG8_LDB(B0, 0, 0); PG8_SCHED; PG8_LDA(At, 0, 0); PG8_STAGE(PG8_SA(1, 1), a1 + hstep, voffA);
;             PG8_WAIT_L(8); PG8_BAR; PG8_WAIT_L(0); PG8_MMA(0, 0, At, B0); PG8_BAR; PG8_SCHED;
;             PG8_LDB(B1, 0, 1); PG8_STAGE(PG8_SB(0, 0), b2, voffB);
;             PG8_BAR; PG8_WAIT_L(0); PG8_MMA(0, 1, At, B1); PG8_BAR;
;             PG8_LDA(At, 0, 1); PG8_STAGE(PG8_SA(0, 0), a2, voffA);
;             PG8_BAR; PG8_WAIT_L(0); PG8_MMA(1, 0, At, B0); PG8_BAR; PG8_SCHED;
;             PG8_STAGE(PG8_SB(0, 1), b2 + hstep, voffB);
;             PG8_WAIT_V(6); PG8_BAR; PG8_MMA(1, 1, At, B1); PG8_BAR;
.LBB0_1122:
	s_barrier
	ds_read_b128 v[128:131], v165
	ds_read_b128 v[132:135], v165 offset:1024
	ds_read_b128 v[136:139], v165 offset:2048
	ds_read_b128 v[140:143], v165 offset:3072
	s_add_u32 s40, s38, 0xfff50080
	s_addc_u32 s41, s39, -1
	s_cmp_eq_u32 s74, 40
	s_cselect_b32 s43, s5, s41
	s_cselect_b32 s42, s4, s40
	s_cselect_b32 s41, s7, s73
	s_cselect_b32 s40, s6, s37
	ds_read_b128 v[168:171], v166
	ds_read_b128 v[172:175], v166 offset:1024
	ds_read_b128 v[176:179], v166 offset:2048
	ds_read_b128 v[180:183], v166 offset:3072
	ds_read_b128 v[184:187], v166 offset:4096
	ds_read_b128 v[188:191], v166 offset:5120
	ds_read_b128 v[192:195], v166 offset:6144
	ds_read_b128 v[196:199], v166 offset:7168
	ds_read_b128 v[200:203], v167
	ds_read_b128 v[204:207], v167 offset:1024
	ds_read_b128 v[208:211], v167 offset:2048
	ds_read_b128 v[212:215], v167 offset:3072
	v_lshl_add_u64 v[252:253], s[38:39], 0, v[154:155]
	s_add_i32 m0, s51, 0xc000
	s_nop 0
	global_load_lds_dwordx4 v[252:253], off
	v_lshl_add_u64 v[252:253], s[38:39], 0, v[156:157]
	s_add_i32 m0, s51, 0xe000
	s_nop 0
	global_load_lds_dwordx4 v[252:253], off
	s_waitcnt vmcnt(8)
	s_waitcnt lgkmcnt(0)
	s_barrier
	s_setprio 1
	v_mfma_f32_16x16x32_bf16 v[124:127], v[128:131], v[168:171], v[124:127]
	v_mfma_f32_16x16x32_bf16 v[120:123], v[136:139], v[168:171], v[120:123]
	v_mfma_f32_16x16x32_bf16 v[116:119], v[128:131], v[176:179], v[116:119]
	v_mfma_f32_16x16x32_bf16 v[112:115], v[136:139], v[176:179], v[112:115]
	v_mfma_f32_16x16x32_bf16 v[108:111], v[128:131], v[184:187], v[108:111]
	v_mfma_f32_16x16x32_bf16 v[96:99], v[136:139], v[184:187], v[96:99]
	v_mfma_f32_16x16x32_bf16 v[80:83], v[128:131], v[192:195], v[80:83]
	v_mfma_f32_16x16x32_bf16 v[72:75], v[136:139], v[192:195], v[72:75]
	v_mfma_f32_16x16x32_bf16 v[124:127], v[132:135], v[172:175], v[124:127]
	v_mfma_f32_16x16x32_bf16 v[120:123], v[140:143], v[172:175], v[120:123]
	v_mfma_f32_16x16x32_bf16 v[116:119], v[132:135], v[180:183], v[116:119]
	v_mfma_f32_16x16x32_bf16 v[112:115], v[140:143], v[180:183], v[112:115]
	v_mfma_f32_16x16x32_bf16 v[108:111], v[132:135], v[188:191], v[108:111]
	v_mfma_f32_16x16x32_bf16 v[96:99], v[140:143], v[188:191], v[96:99]
	v_mfma_f32_16x16x32_bf16 v[80:83], v[132:135], v[196:199], v[80:83]
	v_mfma_f32_16x16x32_bf16 v[72:75], v[140:143], v[196:199], v[72:75]
	v_mfma_f32_16x16x32_bf16 v[104:107], v[200:203], v[168:171], v[104:107]
	v_mfma_f32_16x16x32_bf16 v[100:103], v[208:211], v[168:171], v[100:103]
	v_mfma_f32_16x16x32_bf16 v[92:95], v[200:203], v[176:179], v[92:95]
	v_mfma_f32_16x16x32_bf16 v[88:91], v[208:211], v[176:179], v[88:91]
	v_mfma_f32_16x16x32_bf16 v[84:87], v[200:203], v[184:187], v[84:87]
	v_mfma_f32_16x16x32_bf16 v[76:79], v[208:211], v[184:187], v[76:79]
	v_mfma_f32_16x16x32_bf16 v[68:71], v[200:203], v[192:195], v[68:71]
	v_mfma_f32_16x16x32_bf16 v[64:67], v[208:211], v[192:195], v[64:67]
	v_mfma_f32_16x16x32_bf16 v[104:107], v[204:207], v[172:175], v[104:107]
	v_mfma_f32_16x16x32_bf16 v[100:103], v[212:215], v[172:175], v[100:103]
	v_mfma_f32_16x16x32_bf16 v[92:95], v[204:207], v[180:183], v[92:95]
	v_mfma_f32_16x16x32_bf16 v[88:91], v[212:215], v[180:183], v[88:91]
	v_mfma_f32_16x16x32_bf16 v[84:87], v[204:207], v[188:191], v[84:87]
	v_mfma_f32_16x16x32_bf16 v[76:79], v[212:215], v[188:191], v[76:79]
	v_mfma_f32_16x16x32_bf16 v[68:71], v[204:207], v[196:199], v[68:71]
	v_mfma_f32_16x16x32_bf16 v[64:67], v[212:215], v[196:199], v[64:67]
	s_setprio 0
	s_barrier
	ds_read_b128 v[168:171], v166 offset:16384
	ds_read_b128 v[172:175], v166 offset:17408
	ds_read_b128 v[176:179], v166 offset:18432
	ds_read_b128 v[180:183], v166 offset:19456
	ds_read_b128 v[184:187], v166 offset:20480
	ds_read_b128 v[188:191], v166 offset:21504
	ds_read_b128 v[192:195], v166 offset:22528
	ds_read_b128 v[196:199], v166 offset:23552
	s_add_i32 s75, s64, s50
	v_lshl_add_u64 v[162:163], s[40:41], 0, v[146:147]
	s_mov_b32 m0, s75
	s_nop 0
	global_load_lds_dwordx4 v[162:163], off
	v_lshl_add_u64 v[216:217], s[40:41], 0, v[150:151]
	s_add_i32 m0, s75, 0x2000
	s_nop 0
	global_load_lds_dwordx4 v[216:217], off
	s_mov_b32 m0, s51
	v_lshl_add_u64 v[218:219], s[42:43], 0, v[144:145]
	global_load_lds_dwordx4 v[218:219], off
	v_lshl_add_u64 v[220:221], s[42:43], 0, v[148:149]
	s_mov_b32 m0, s52
	s_nop 0
	global_load_lds_dwordx4 v[220:221], off
	s_add_u32 s76, s40, 0xb0000
	s_addc_u32 s77, s41, 0
	s_add_i32 s75, s65, s50
	v_lshl_add_u64 v[254:255], s[76:77], 0, v[146:147]
	s_mov_b32 m0, s75
	s_nop 0
	global_load_lds_dwordx4 v[254:255], off
	v_lshl_add_u64 v[254:255], s[76:77], 0, v[150:151]
	s_add_i32 m0, s75, 0x2000
	s_nop 0
	global_load_lds_dwordx4 v[254:255], off
	s_waitcnt vmcnt(8)
	s_waitcnt lgkmcnt(0)
	s_barrier
; #define PG8_STAGE(bufoff, gbase, voff) do { _Pragma("unroll") for (int _i = 0; _i < 2; ++_i) \
;         __builtin_amdgcn_global_load_lds((const unsigned*)((const char*)(gbase) + (voff)[_i]), (LAS unsigned*)(lds + (bufoff) + ldsw + _i * 8192), 16, 0, 0); } while (0)
; #define PG8_LDA(dst, b, h) do { _Pragma("unroll") for (int m = 0; m < 4; ++m) _Pragma("unroll") for (int k = 0; k < 2; ++k) dst[m][k] = *(const LAS bf16x8*)(lds + PG8_SA(b, h) + aoff + m * 2048 + k * 1024); } while (0)
; #define PG8_LDB(dst, b, h) do { _Pragma("unroll") for (int n = 0; n < 2; ++n) _Pragma("unroll") for (int k = 0; k < 2; ++k) dst[n][k] = *(const LAS bf16x8*)(lds + PG8_SB(b, h) + boff + n * 2048 + k * 1024); } while (0)
; #define PG8_MMA(ai, bj, At, Bt) do { __builtin_amdgcn_s_setprio(1); _Pragma("unroll") for (int m = 0; m < 4; ++m) _Pragma("unroll") for (int n = 0; n < 2; ++n) _Pragma("unroll") for (int k = 0; k < 2; ++k) \
;         acc[ai][bj][m][n] = __builtin_amdgcn_mfma_f32_16x16x32_bf16(Bt[n][k], At[m][k], acc[ai][bj][m][n], 0, 0, 0); __builtin_amdgcn_s_setprio(0); } while (0)
; #define PG8_WAIT_V(n) asm volatile("s_waitcnt vmcnt(" #n ")" ::: "memory")
; #define PG8_WAIT_L(n) asm volatile("s_waitcnt lgkmcnt(" #n ")" ::: "memory")
; #define PG8_BAR __builtin_amdgcn_s_barrier()
; #define PG8_SCHED __builtin_amdgcn_sched_barrier(0)
; template <class Epi>
; __device__ __forceinline__ void gemm_phase(LAS unsigned char* lds, const Gemm g, const StaticOrder& S, const Epi& E, int wv) {
;     ...
;             PG8_BAR; PG8_WAIT_L(0); PG8_MMA(0, 1, At, B1); PG8_BAR;
;             PG8_LDA(At, 0, 1); PG8_STAGE(PG8_SA(0, 0), a2, voffA);
;             PG8_BAR; PG8_WAIT_L(0); PG8_MMA(1, 0, At, B0); PG8_BAR; PG8_SCHED;
;             PG8_STAGE(PG8_SB(0, 1), b2 + hstep, voffB);
;             PG8_WAIT_V(6); PG8_BAR; PG8_MMA(1, 1, At, B1); PG8_BAR;
;             PG8_LDB(B0, 1, 0); PG8_SCHED; PG8_LDA(At, 1, 0); PG8_STAGE(PG8_SA(0, 1), a2 + hstep, voffA);
;             PG8_WAIT_L(8); PG8_BAR; PG8_WAIT_L(0); PG8_MMA(0, 0, At, B0); PG8_BAR; PG8_SCHED;
;             PG8_LDB(B1, 1, 1); PG8_STAGE(PG8_SB(1, 0), b3, voffB);
;             PG8_BAR; PG8_WAIT_L(0); PG8_MMA(0, 1, At, B1); PG8_BAR;
	s_setprio 1
	v_mfma_f32_16x16x32_bf16 v[60:63], v[128:131], v[168:171], v[60:63]
	v_mfma_f32_16x16x32_bf16 v[56:59], v[136:139], v[168:171], v[56:59]
	v_mfma_f32_16x16x32_bf16 v[48:51], v[128:131], v[176:179], v[48:51]
	v_mfma_f32_16x16x32_bf16 v[40:43], v[136:139], v[176:179], v[40:43]
	v_mfma_f32_16x16x32_bf16 v[32:35], v[128:131], v[184:187], v[32:35]
	v_mfma_f32_16x16x32_bf16 v[24:27], v[136:139], v[184:187], v[24:27]
	v_mfma_f32_16x16x32_bf16 v[16:19], v[128:131], v[192:195], v[16:19]
	v_mfma_f32_16x16x32_bf16 v[8:11], v[136:139], v[192:195], v[8:11]
	v_mfma_f32_16x16x32_bf16 v[60:63], v[132:135], v[172:175], v[60:63]
	v_mfma_f32_16x16x32_bf16 v[56:59], v[140:143], v[172:175], v[56:59]
	v_mfma_f32_16x16x32_bf16 v[48:51], v[132:135], v[180:183], v[48:51]
	v_mfma_f32_16x16x32_bf16 v[40:43], v[140:143], v[180:183], v[40:43]
	v_mfma_f32_16x16x32_bf16 v[32:35], v[132:135], v[188:191], v[32:35]
	v_mfma_f32_16x16x32_bf16 v[24:27], v[140:143], v[188:191], v[24:27]
	v_mfma_f32_16x16x32_bf16 v[16:19], v[132:135], v[196:199], v[16:19]
	v_mfma_f32_16x16x32_bf16 v[8:11], v[140:143], v[196:199], v[8:11]
	v_mfma_f32_16x16x32_bf16 v[52:55], v[200:203], v[168:171], v[52:55]
	v_mfma_f32_16x16x32_bf16 v[44:47], v[208:211], v[168:171], v[44:47]
	v_mfma_f32_16x16x32_bf16 v[36:39], v[200:203], v[176:179], v[36:39]
	v_mfma_f32_16x16x32_bf16 v[28:31], v[208:211], v[176:179], v[28:31]
	v_mfma_f32_16x16x32_bf16 v[20:23], v[200:203], v[184:187], v[20:23]
	v_mfma_f32_16x16x32_bf16 v[12:15], v[208:211], v[184:187], v[12:15]
	v_mfma_f32_16x16x32_bf16 v[4:7], v[200:203], v[192:195], v[4:7]
	v_mfma_f32_16x16x32_bf16 v[0:3], v[208:211], v[192:195], v[0:3]
	v_mfma_f32_16x16x32_bf16 v[52:55], v[204:207], v[172:175], v[52:55]
	v_mfma_f32_16x16x32_bf16 v[44:47], v[212:215], v[172:175], v[44:47]
	v_mfma_f32_16x16x32_bf16 v[36:39], v[204:207], v[180:183], v[36:39]
	v_mfma_f32_16x16x32_bf16 v[28:31], v[212:215], v[180:183], v[28:31]
	v_mfma_f32_16x16x32_bf16 v[20:23], v[204:207], v[188:191], v[20:23]
	v_mfma_f32_16x16x32_bf16 v[12:15], v[212:215], v[188:191], v[12:15]
	v_mfma_f32_16x16x32_bf16 v[4:7], v[204:207], v[196:199], v[4:7]
	v_mfma_f32_16x16x32_bf16 v[0:3], v[212:215], v[196:199], v[0:3]
	s_setprio 0
	s_add_i32 s75, 0, 0x18000
	v_add_u32_e32 v140, s75, v164
	s_barrier
	ds_read_b128 v[128:131], v140
	ds_read_b128 v[132:135], v140 offset:1024
	ds_read_b128 v[136:139], v140 offset:2048
	ds_read_b128 v[140:143], v140 offset:3072
	s_add_u32 s42, s42, 0xb0000
	s_addc_u32 s43, s43, 0
	ds_read_b128 v[168:171], v166 offset:32768
	ds_read_b128 v[172:175], v166 offset:33792
	ds_read_b128 v[176:179], v166 offset:34816
	ds_read_b128 v[180:183], v166 offset:35840
	ds_read_b128 v[184:187], v166 offset:36864
	ds_read_b128 v[188:191], v166 offset:37888
	ds_read_b128 v[192:195], v166 offset:38912
	ds_read_b128 v[196:199], v166 offset:39936
	s_mov_b32 m0, s53
	v_lshl_add_u64 v[252:253], s[42:43], 0, v[144:145]
	global_load_lds_dwordx4 v[252:253], off
	v_lshl_add_u64 v[252:253], s[42:43], 0, v[148:149]
	s_mov_b32 m0, s54
	s_nop 0
	global_load_lds_dwordx4 v[252:253], off
	s_add_i32 s42, 0, 0x1c000
	v_add_u32_e32 v152, s42, v164
	ds_read_b128 v[200:203], v152
	ds_read_b128 v[204:207], v152 offset:1024
	ds_read_b128 v[208:211], v152 offset:2048
	ds_read_b128 v[212:215], v152 offset:3072
	s_waitcnt vmcnt(8)
	s_waitcnt lgkmcnt(0)
	s_barrier
	s_setprio 1
	v_mfma_f32_16x16x32_bf16 v[124:127], v[128:131], v[168:171], v[124:127]
	v_mfma_f32_16x16x32_bf16 v[120:123], v[136:139], v[168:171], v[120:123]
	v_mfma_f32_16x16x32_bf16 v[116:119], v[128:131], v[176:179], v[116:119]
	v_mfma_f32_16x16x32_bf16 v[112:115], v[136:139], v[176:179], v[112:115]
	v_mfma_f32_16x16x32_bf16 v[108:111], v[128:131], v[184:187], v[108:111]
	v_mfma_f32_16x16x32_bf16 v[96:99], v[136:139], v[184:187], v[96:99]
	v_mfma_f32_16x16x32_bf16 v[80:83], v[128:131], v[192:195], v[80:83]
	v_mfma_f32_16x16x32_bf16 v[72:75], v[136:139], v[192:195], v[72:75]
	v_mfma_f32_16x16x32_bf16 v[124:127], v[132:135], v[172:175], v[124:127]
	v_mfma_f32_16x16x32_bf16 v[120:123], v[140:143], v[172:175], v[120:123]
	v_mfma_f32_16x16x32_bf16 v[116:119], v[132:135], v[180:183], v[116:119]
	v_mfma_f32_16x16x32_bf16 v[112:115], v[140:143], v[180:183], v[112:115]
	v_mfma_f32_16x16x32_bf16 v[108:111], v[132:135], v[188:191], v[108:111]
	v_mfma_f32_16x16x32_bf16 v[96:99], v[140:143], v[188:191], v[96:99]
	v_mfma_f32_16x16x32_bf16 v[80:83], v[132:135], v[196:199], v[80:83]
	v_mfma_f32_16x16x32_bf16 v[72:75], v[140:143], v[196:199], v[72:75]
	v_mfma_f32_16x16x32_bf16 v[104:107], v[200:203], v[168:171], v[104:107]
	v_mfma_f32_16x16x32_bf16 v[100:103], v[208:211], v[168:171], v[100:103]
	v_mfma_f32_16x16x32_bf16 v[92:95], v[200:203], v[176:179], v[92:95]
	v_mfma_f32_16x16x32_bf16 v[88:91], v[208:211], v[176:179], v[88:91]
	v_mfma_f32_16x16x32_bf16 v[84:87], v[200:203], v[184:187], v[84:87]
	v_mfma_f32_16x16x32_bf16 v[76:79], v[208:211], v[184:187], v[76:79]
	v_mfma_f32_16x16x32_bf16 v[68:71], v[200:203], v[192:195], v[68:71]
	v_mfma_f32_16x16x32_bf16 v[64:67], v[208:211], v[192:195], v[64:67]
	v_mfma_f32_16x16x32_bf16 v[104:107], v[204:207], v[172:175], v[104:107]
	v_mfma_f32_16x16x32_bf16 v[100:103], v[212:215], v[172:175], v[100:103]
	v_mfma_f32_16x16x32_bf16 v[92:95], v[204:207], v[180:183], v[92:95]
	v_mfma_f32_16x16x32_bf16 v[88:91], v[212:215], v[180:183], v[88:91]
	v_mfma_f32_16x16x32_bf16 v[84:87], v[204:207], v[188:191], v[84:87]
	v_mfma_f32_16x16x32_bf16 v[76:79], v[212:215], v[188:191], v[76:79]
	v_mfma_f32_16x16x32_bf16 v[68:71], v[204:207], v[196:199], v[68:71]
	v_mfma_f32_16x16x32_bf16 v[64:67], v[212:215], v[196:199], v[64:67]
	s_setprio 0
	s_barrier
; __device__ __forceinline__ int lane_fresh() { unsigned m = ~0u; asm volatile("" : "+s"(m)); return (int)__builtin_amdgcn_mbcnt_hi(m, __builtin_amdgcn_mbcnt_lo(m, 0u)); }
; __device__ __forceinline__ unsigned pk2(float lo, float hi) { unsigned r; asm("v_cvt_pk_bf16_f32 %0, %1, %2" : "=v"(r) : "v"(lo), "v"(hi)); return r; }
; #define PG8_STAGE(bufoff, gbase, voff) do { _Pragma("unroll") for (int _i = 0; _i < 2; ++_i) \
;         __builtin_amdgcn_global_load_lds((const unsigned*)((const char*)(gbase) + (voff)[_i]), (LAS unsigned*)(lds + (bufoff) + ldsw + _i * 8192), 16, 0, 0); } while (0)
; #define PG8_BAR __builtin_amdgcn_s_barrier()
; template <class Epi>
; __device__ __forceinline__ void gemm_phase(LAS unsigned char* lds, const Gemm g, const StaticOrder& S, const Epi& E, int wv) {
;     ...
;             PG8_LDB(B1, 1, 1); PG8_STAGE(PG8_SB(1, 0), b3, voffB);
;             PG8_BAR; PG8_WAIT_L(0); PG8_MMA(0, 1, At, B1); PG8_BAR;
;             PG8_LDA(At, 1, 1); PG8_STAGE(PG8_SA(1, 0), a3, voffA);
;             PG8_BAR; PG8_WAIT_L(0); PG8_MMA(1, 0, At, B0); PG8_BAR; PG8_SCHED;
;             PG8_STAGE(PG8_SB(1, 1), b3 + hstep, voffB);
;             PG8_WAIT_V(6); PG8_BAR; PG8_MMA(1, 1, At, B1); PG8_BAR;
;         }
;         { const int ln2 = lane_fresh();
;           E(acc, cur, wr, wc, ln2 & 15, ln2 >> 4); }
;         if (!has_next) break;
;     __device__ __forceinline__ void operator()(const f32x4 (&acc)[2][2][4][2], const Unit& u, int wr, int wc, int fr, int fq) const {
;         const float* gate = (u.pm >= 64) ? gate1 : gate0;
;         f32x4 gv[2][2];
; #pragma unroll
;         for (int bj = 0; bj < 2; ++bj)
; #pragma unroll
;             for (int n = 0; n < 2; ++n) gv[bj][n] = *(const f32x4*)(gate + u.pn * 256 + bj * 128 + wc * 32 + n * 16 + 4 * fq);
; #pragma unroll
;         for (int ai = 0; ai < 2; ++ai)
; #pragma unroll
;             for (int m = 0; m < 4; ++m) {
;                 const size_t row = (size_t)u.pm * 256 + ai * 128 + wr * 64 + 4 * fr + m;
; #pragma unroll
;                 for (int bj = 0; bj < 2; ++bj)
; #pragma unroll
;                     for (int n = 0; n < 2; ++n) {
;                         const f32x4 v = gv[bj][n] * acc[ai][bj][m][n];
;                         u32x2 w; w.x = pk2(v[0], v[1]); w.y = pk2(v[2], v[3]);
;                         *(u32x2*)(O + row * D + u.pn * 256 + bj * 128 + wc * 32 + n * 16 + 4 * fq) = w;
	ds_read_b128 v[168:171], v166 offset:49152
	ds_read_b128 v[172:175], v166 offset:50176
	ds_read_b128 v[176:179], v166 offset:51200
	ds_read_b128 v[180:183], v166 offset:52224
	ds_read_b128 v[184:187], v166 offset:53248
	ds_read_b128 v[188:191], v166 offset:54272
	ds_read_b128 v[192:195], v166 offset:55296
	ds_read_b128 v[196:199], v166 offset:56320
	s_add_i32 s43, s75, s50
	v_lshl_add_u64 v[162:163], v[162:163], 0, s[16:17]
	s_mov_b32 m0, s43
	s_nop 0
	global_load_lds_dwordx4 v[162:163], off
	v_lshl_add_u64 v[162:163], v[216:217], 0, s[16:17]
	s_add_i32 m0, s43, 0x2000
	s_nop 0
	global_load_lds_dwordx4 v[162:163], off
	s_mov_b32 m0, s57
	v_lshl_add_u64 v[162:163], v[218:219], 0, s[16:17]
	global_load_lds_dwordx4 v[162:163], off
	v_lshl_add_u64 v[162:163], v[220:221], 0, s[16:17]
	s_mov_b32 m0, s58
	s_nop 0
	global_load_lds_dwordx4 v[162:163], off
	s_add_u32 s40, s40, 0xb0080
	s_addc_u32 s41, s41, 0
	s_add_i32 s42, s42, s50
	v_lshl_add_u64 v[254:255], s[40:41], 0, v[146:147]
	s_mov_b32 m0, s42
	s_nop 0
	global_load_lds_dwordx4 v[254:255], off
	v_lshl_add_u64 v[254:255], s[40:41], 0, v[150:151]
	s_add_i32 m0, s42, 0x2000
	s_nop 0
	global_load_lds_dwordx4 v[254:255], off
	s_waitcnt vmcnt(8)
	s_waitcnt lgkmcnt(0)
	s_barrier
	s_setprio 1
	v_mfma_f32_16x16x32_bf16 v[60:63], v[128:131], v[168:171], v[60:63]
	v_mfma_f32_16x16x32_bf16 v[56:59], v[136:139], v[168:171], v[56:59]
	v_mfma_f32_16x16x32_bf16 v[48:51], v[128:131], v[176:179], v[48:51]
	v_mfma_f32_16x16x32_bf16 v[40:43], v[136:139], v[176:179], v[40:43]
	v_mfma_f32_16x16x32_bf16 v[32:35], v[128:131], v[184:187], v[32:35]
	v_mfma_f32_16x16x32_bf16 v[24:27], v[136:139], v[184:187], v[24:27]
	v_mfma_f32_16x16x32_bf16 v[16:19], v[128:131], v[192:195], v[16:19]
	v_mfma_f32_16x16x32_bf16 v[8:11], v[136:139], v[192:195], v[8:11]
	v_mfma_f32_16x16x32_bf16 v[60:63], v[132:135], v[172:175], v[60:63]
	v_mfma_f32_16x16x32_bf16 v[56:59], v[140:143], v[172:175], v[56:59]
	v_mfma_f32_16x16x32_bf16 v[48:51], v[132:135], v[180:183], v[48:51]
	v_mfma_f32_16x16x32_bf16 v[40:43], v[140:143], v[180:183], v[40:43]
	v_mfma_f32_16x16x32_bf16 v[32:35], v[132:135], v[188:191], v[32:35]
	v_mfma_f32_16x16x32_bf16 v[24:27], v[140:143], v[188:191], v[24:27]
	v_mfma_f32_16x16x32_bf16 v[16:19], v[132:135], v[196:199], v[16:19]
	v_mfma_f32_16x16x32_bf16 v[8:11], v[140:143], v[196:199], v[8:11]
	v_mfma_f32_16x16x32_bf16 v[52:55], v[200:203], v[168:171], v[52:55]
	v_mfma_f32_16x16x32_bf16 v[44:47], v[208:211], v[168:171], v[44:47]
	v_mfma_f32_16x16x32_bf16 v[36:39], v[200:203], v[176:179], v[36:39]
	v_mfma_f32_16x16x32_bf16 v[28:31], v[208:211], v[176:179], v[28:31]
	v_mfma_f32_16x16x32_bf16 v[20:23], v[200:203], v[184:187], v[20:23]
	v_mfma_f32_16x16x32_bf16 v[12:15], v[208:211], v[184:187], v[12:15]
	v_mfma_f32_16x16x32_bf16 v[4:7], v[200:203], v[192:195], v[4:7]
	v_mfma_f32_16x16x32_bf16 v[0:3], v[208:211], v[192:195], v[0:3]
	v_mfma_f32_16x16x32_bf16 v[52:55], v[204:207], v[172:175], v[52:55]
	v_mfma_f32_16x16x32_bf16 v[44:47], v[212:215], v[172:175], v[44:47]
	v_mfma_f32_16x16x32_bf16 v[36:39], v[204:207], v[180:183], v[36:39]
	v_mfma_f32_16x16x32_bf16 v[28:31], v[212:215], v[180:183], v[28:31]
	v_mfma_f32_16x16x32_bf16 v[20:23], v[204:207], v[188:191], v[20:23]
	v_mfma_f32_16x16x32_bf16 v[12:15], v[212:215], v[188:191], v[12:15]
	v_mfma_f32_16x16x32_bf16 v[4:7], v[204:207], v[196:199], v[4:7]
	v_mfma_f32_16x16x32_bf16 v[0:3], v[212:215], v[196:199], v[0:3]
	s_setprio 0
	s_add_i32 s74, s74, 2
	s_add_u32 s38, s38, 0x100
	s_addc_u32 s39, s39, 0
	s_add_u32 s37, s37, 0x100
	s_addc_u32 s73, s73, 0
	s_cmp_gt_u32 s74, 41
	s_cbranch_scc0 .LBB0_1122
	s_barrier
	s_mov_b32 s37, -1
	s_cmp_gt_i32 s36, 63
	v_mbcnt_lo_u32_b32 v128, s37, 0
	v_mbcnt_hi_u32_b32 v152, s37, v128
	s_cselect_b32 s37, s66, 0x1645000
	s_add_u32 s37, s10, s37
	s_addc_u32 s42, s11, 0
	s_lshl_b32 s38, s12, 8
	s_ashr_i32 s39, s38, 31
	s_lshl_b64 s[40:41], s[38:39], 2
	s_add_u32 s12, s37, s40
	s_addc_u32 s37, s42, s41
	s_lshl_b32 s40, s56, 2
	v_lshrrev_b32_e32 v128, 2, v152
	s_add_u32 s40, s12, s40
	v_and_b32_e32 v162, 28, v128
	s_addc_u32 s41, s37, 0
	v_lshlrev_b32_e32 v128, 2, v162
	s_nop 0
	s_ashr_i32 s37, s36, 31
	s_lshl_b64 s[36:37], s[36:37], 8
	s_add_u32 s12, s36, s55
	v_lshlrev_b32_e32 v163, 2, v152
	s_addc_u32 s36, s37, s59
	v_bfe_u32 v222, v152, 5, 1
	v_bfe_u32 v152, v152, 4, 1
	v_lshlrev_b32_e32 v222, 4, v222
	v_lshl_or_b32 v152, v152, 5, v222
	v_and_or_b32 v162, v163, 60, s12
	v_mov_b32_e32 v163, s36
	v_lshlrev_b64 v[162:163], 11, v[162:163]
	v_lshl_add_u64 v[162:163], s[14:15], 0, v[162:163]
	s_lshl_b32 s12, s56, 1
	v_lshl_add_u64 v[162:163], s[38:39], 1, v[162:163]
	v_lshl_add_u64 v[162:163], v[162:163], 0, s[12:13]
	v_lshl_add_u64 v[162:163], v[162:163], 0, v[152:153]
	v_lshl_add_u64 v[168:169], v[162:163], 0, s[18:19]
	v_lshl_add_u64 v[170:171], v[162:163], 0, s[22:23]
	s_mov_b32 s12, s71
	s_nop 0
	v_lshl_add_u64 v[222:223], v[162:163], 0, s[30:31]
	s_mov_b32 s36, s72
	s_mov_b64 s[40:41], s[6:7]
	s_mov_b64 s[38:39], s[4:5]
	v_pk_mul_f32 v[124:125], v[124:125], v[236:237]
	v_pk_mul_f32 v[126:127], v[126:127], v[238:239]
	v_pk_mul_f32 v[120:121], v[120:121], v[232:233]
	v_pk_mul_f32 v[122:123], v[122:123], v[234:235]
	v_cvt_pk_bf16_f32 v124, v124, v125
	v_cvt_pk_bf16_f32 v125, v126, v127
	v_cvt_pk_bf16_f32 v126, v120, v121
	v_cvt_pk_bf16_f32 v127, v122, v123
	v_pk_mul_f32 v[104:105], v[104:105], v[228:229]
	v_pk_mul_f32 v[106:107], v[106:107], v[230:231]
	v_pk_mul_f32 v[100:101], v[100:101], v[224:225]
	v_pk_mul_f32 v[102:103], v[102:103], v[226:227]
	v_permlane16_swap_b32_e32 v124, v126
	v_permlane16_swap_b32_e32 v125, v127
; __device__ __forceinline__ unsigned pk2(float lo, float hi) { unsigned r; asm("v_cvt_pk_bf16_f32 %0, %1, %2" : "=v"(r) : "v"(lo), "v"(hi)); return r; }
; #define PG8_WAIT_V(n) asm volatile("s_waitcnt vmcnt(" #n ")" ::: "memory")
; #define PG8_BAR __builtin_amdgcn_s_barrier()
; template <class Epi>
; __device__ __forceinline__ void gemm_phase(LAS unsigned char* lds, const Gemm g, const StaticOrder& S, const Epi& E, int wv) {
;     ...
;         if (!has_next) break;
; #pragma unroll
;         for (int a = 0; a < 2; ++a)
; #pragma unroll
;             for (int b = 0; b < 2; ++b)
; #pragma unroll
;                 for (int m = 0; m < 4; ++m)
; #pragma unroll
;                     for (int n = 0; n < 2; ++n) acc[a][b][m][n] = (f32x4){0.f, 0.f, 0.f, 0.f};
;         cur = nxt; cA = nA; cB = nB; ++ui;
;     }
;     PG8_WAIT_V(0);
;     if (wr == 0) PG8_BAR;
;     PG8_BAR;
;     __device__ __forceinline__ void operator()(const f32x4 (&acc)[2][2][4][2], const Unit& u, int wr, int wc, int fr, int fq) const {
;     ...
;         for (int ai = 0; ai < 2; ++ai)
; #pragma unroll
;             for (int m = 0; m < 4; ++m) {
;                 const size_t row = (size_t)u.pm * 256 + ai * 128 + wr * 64 + 4 * fr + m;
; #pragma unroll
;                 for (int bj = 0; bj < 2; ++bj)
; #pragma unroll
;                     for (int n = 0; n < 2; ++n) {
;                         const f32x4 v = gv[bj][n] * acc[ai][bj][m][n];
;                         u32x2 w; w.x = pk2(v[0], v[1]); w.y = pk2(v[2], v[3]);
;                         *(u32x2*)(O + row * D + u.pn * 256 + bj * 128 + wc * 32 + n * 16 + 4 * fq) = w;
;                     }
;             }
	global_store_dwordx4 v[162:163], v[124:127], off
	v_cvt_pk_bf16_f32 v104, v104, v105
	v_cvt_pk_bf16_f32 v105, v106, v107
	v_cvt_pk_bf16_f32 v106, v100, v101
	v_cvt_pk_bf16_f32 v107, v102, v103
	v_pk_mul_f32 v[116:117], v[116:117], v[236:237]
	v_pk_mul_f32 v[118:119], v[118:119], v[238:239]
	v_pk_mul_f32 v[112:113], v[112:113], v[232:233]
	v_pk_mul_f32 v[114:115], v[114:115], v[234:235]
	v_permlane16_swap_b32_e32 v104, v106
	v_permlane16_swap_b32_e32 v105, v107
	global_store_dwordx4 v[162:163], v[104:107], off offset:256
	v_cvt_pk_bf16_f32 v116, v116, v117
	v_cvt_pk_bf16_f32 v117, v118, v119
	v_cvt_pk_bf16_f32 v118, v112, v113
	v_cvt_pk_bf16_f32 v119, v114, v115
	v_pk_mul_f32 v[92:93], v[92:93], v[228:229]
	v_pk_mul_f32 v[94:95], v[94:95], v[230:231]
	v_pk_mul_f32 v[88:89], v[88:89], v[224:225]
	v_pk_mul_f32 v[90:91], v[90:91], v[226:227]
	v_permlane16_swap_b32_e32 v116, v118
	v_permlane16_swap_b32_e32 v117, v119
	global_store_dwordx4 v[162:163], v[116:119], off offset:2048
	v_cvt_pk_bf16_f32 v92, v92, v93
	v_cvt_pk_bf16_f32 v93, v94, v95
	v_cvt_pk_bf16_f32 v94, v88, v89
	v_cvt_pk_bf16_f32 v95, v90, v91
	v_pk_mul_f32 v[108:109], v[108:109], v[236:237]
	v_pk_mul_f32 v[110:111], v[110:111], v[238:239]
	v_pk_mul_f32 v[96:97], v[96:97], v[232:233]
	v_pk_mul_f32 v[98:99], v[98:99], v[234:235]
	v_permlane16_swap_b32_e32 v92, v94
	v_permlane16_swap_b32_e32 v93, v95
	global_store_dwordx4 v[162:163], v[92:95], off offset:2304
	v_cvt_pk_bf16_f32 v108, v108, v109
	v_cvt_pk_bf16_f32 v109, v110, v111
	v_cvt_pk_bf16_f32 v110, v96, v97
	v_cvt_pk_bf16_f32 v111, v98, v99
	v_pk_mul_f32 v[84:85], v[84:85], v[228:229]
	v_pk_mul_f32 v[86:87], v[86:87], v[230:231]
	v_pk_mul_f32 v[76:77], v[76:77], v[224:225]
	v_pk_mul_f32 v[78:79], v[78:79], v[226:227]
	v_permlane16_swap_b32_e32 v108, v110
	v_permlane16_swap_b32_e32 v109, v111
	global_store_dwordx4 v[168:169], v[108:111], off
	v_cvt_pk_bf16_f32 v84, v84, v85
	v_cvt_pk_bf16_f32 v85, v86, v87
	v_cvt_pk_bf16_f32 v86, v76, v77
	v_cvt_pk_bf16_f32 v87, v78, v79
	v_pk_mul_f32 v[80:81], v[80:81], v[236:237]
	v_pk_mul_f32 v[82:83], v[82:83], v[238:239]
	v_pk_mul_f32 v[72:73], v[72:73], v[232:233]
	v_pk_mul_f32 v[74:75], v[74:75], v[234:235]
	v_permlane16_swap_b32_e32 v84, v86
	v_permlane16_swap_b32_e32 v85, v87
	global_store_dwordx4 v[168:169], v[84:87], off offset:256
	v_cvt_pk_bf16_f32 v80, v80, v81
	v_cvt_pk_bf16_f32 v81, v82, v83
	v_cvt_pk_bf16_f32 v82, v72, v73
	v_cvt_pk_bf16_f32 v83, v74, v75
	v_pk_mul_f32 v[68:69], v[68:69], v[228:229]
	v_pk_mul_f32 v[70:71], v[70:71], v[230:231]
	v_pk_mul_f32 v[64:65], v[64:65], v[224:225]
	v_pk_mul_f32 v[66:67], v[66:67], v[226:227]
	v_permlane16_swap_b32_e32 v80, v82
	v_permlane16_swap_b32_e32 v81, v83
	global_store_dwordx4 v[168:169], v[80:83], off offset:2048
	v_cvt_pk_bf16_f32 v68, v68, v69
	v_cvt_pk_bf16_f32 v69, v70, v71
	v_cvt_pk_bf16_f32 v70, v64, v65
	v_cvt_pk_bf16_f32 v71, v66, v67
	v_pk_mul_f32 v[60:61], v[60:61], v[236:237]
	v_pk_mul_f32 v[62:63], v[62:63], v[238:239]
	v_pk_mul_f32 v[56:57], v[56:57], v[232:233]
	v_pk_mul_f32 v[58:59], v[58:59], v[234:235]
	v_permlane16_swap_b32_e32 v68, v70
	v_permlane16_swap_b32_e32 v69, v71
	global_store_dwordx4 v[168:169], v[68:71], off offset:2304
	v_cvt_pk_bf16_f32 v60, v60, v61
	v_cvt_pk_bf16_f32 v61, v62, v63
	v_cvt_pk_bf16_f32 v62, v56, v57
	v_cvt_pk_bf16_f32 v63, v58, v59
	v_pk_mul_f32 v[52:53], v[52:53], v[228:229]
	v_pk_mul_f32 v[54:55], v[54:55], v[230:231]
	v_pk_mul_f32 v[44:45], v[44:45], v[224:225]
	v_pk_mul_f32 v[46:47], v[46:47], v[226:227]
	v_permlane16_swap_b32_e32 v60, v62
	v_permlane16_swap_b32_e32 v61, v63
	global_store_dwordx4 v[170:171], v[60:63], off
	v_cvt_pk_bf16_f32 v52, v52, v53
	v_cvt_pk_bf16_f32 v53, v54, v55
	v_cvt_pk_bf16_f32 v54, v44, v45
	v_cvt_pk_bf16_f32 v55, v46, v47
	v_pk_mul_f32 v[48:49], v[48:49], v[236:237]
	v_pk_mul_f32 v[50:51], v[50:51], v[238:239]
	v_pk_mul_f32 v[40:41], v[40:41], v[232:233]
	v_pk_mul_f32 v[42:43], v[42:43], v[234:235]
	v_permlane16_swap_b32_e32 v52, v54
	v_permlane16_swap_b32_e32 v53, v55
	global_store_dwordx4 v[170:171], v[52:55], off offset:256
	v_cvt_pk_bf16_f32 v48, v48, v49
	v_cvt_pk_bf16_f32 v49, v50, v51
	v_cvt_pk_bf16_f32 v50, v40, v41
	v_cvt_pk_bf16_f32 v51, v42, v43
	v_pk_mul_f32 v[36:37], v[36:37], v[228:229]
	v_pk_mul_f32 v[38:39], v[38:39], v[230:231]
	v_pk_mul_f32 v[28:29], v[28:29], v[224:225]
	v_pk_mul_f32 v[30:31], v[30:31], v[226:227]
	v_permlane16_swap_b32_e32 v48, v50
	v_permlane16_swap_b32_e32 v49, v51
	global_store_dwordx4 v[170:171], v[48:51], off offset:2048
	v_cvt_pk_bf16_f32 v36, v36, v37
	v_cvt_pk_bf16_f32 v37, v38, v39
	v_cvt_pk_bf16_f32 v38, v28, v29
	v_cvt_pk_bf16_f32 v39, v30, v31
	v_pk_mul_f32 v[32:33], v[32:33], v[236:237]
	v_pk_mul_f32 v[34:35], v[34:35], v[238:239]
	v_pk_mul_f32 v[24:25], v[24:25], v[232:233]
	v_pk_mul_f32 v[26:27], v[26:27], v[234:235]
	v_permlane16_swap_b32_e32 v36, v38
	v_permlane16_swap_b32_e32 v37, v39
	global_store_dwordx4 v[170:171], v[36:39], off offset:2304
	v_cvt_pk_bf16_f32 v32, v32, v33
	v_cvt_pk_bf16_f32 v33, v34, v35
	v_cvt_pk_bf16_f32 v34, v24, v25
	v_cvt_pk_bf16_f32 v35, v26, v27
	v_pk_mul_f32 v[20:21], v[20:21], v[228:229]
	v_pk_mul_f32 v[22:23], v[22:23], v[230:231]
	v_pk_mul_f32 v[12:13], v[12:13], v[224:225]
	v_pk_mul_f32 v[14:15], v[14:15], v[226:227]
	v_permlane16_swap_b32_e32 v32, v34
	v_permlane16_swap_b32_e32 v33, v35
	global_store_dwordx4 v[222:223], v[32:35], off
	v_cvt_pk_bf16_f32 v20, v20, v21
	v_cvt_pk_bf16_f32 v21, v22, v23
	v_cvt_pk_bf16_f32 v22, v12, v13
	v_cvt_pk_bf16_f32 v23, v14, v15
	v_pk_mul_f32 v[16:17], v[16:17], v[236:237]
	v_pk_mul_f32 v[18:19], v[18:19], v[238:239]
	v_pk_mul_f32 v[8:9], v[8:9], v[232:233]
	v_pk_mul_f32 v[10:11], v[10:11], v[234:235]
	v_permlane16_swap_b32_e32 v20, v22
	v_permlane16_swap_b32_e32 v21, v23
	global_store_dwordx4 v[222:223], v[20:23], off offset:256
	v_cvt_pk_bf16_f32 v16, v16, v17
	v_cvt_pk_bf16_f32 v17, v18, v19
	v_cvt_pk_bf16_f32 v18, v8, v9
	v_cvt_pk_bf16_f32 v19, v10, v11
	v_pk_mul_f32 v[4:5], v[4:5], v[228:229]
	v_pk_mul_f32 v[6:7], v[6:7], v[230:231]
	v_pk_mul_f32 v[0:1], v[0:1], v[224:225]
	v_pk_mul_f32 v[2:3], v[2:3], v[226:227]
	v_permlane16_swap_b32_e32 v16, v18
	v_permlane16_swap_b32_e32 v17, v19
	global_store_dwordx4 v[222:223], v[16:19], off offset:2048
	v_cvt_pk_bf16_f32 v4, v4, v5
	v_cvt_pk_bf16_f32 v5, v6, v7
	v_cvt_pk_bf16_f32 v6, v0, v1
	v_cvt_pk_bf16_f32 v7, v2, v3
	s_nop 1
	v_permlane16_swap_b32_e32 v4, v6
	v_permlane16_swap_b32_e32 v5, v7
	global_store_dwordx4 v[222:223], v[4:7], off offset:2304
	s_and_b64 vcc, exec, s[8:9]
	s_cbranch_vccz .LBB0_1111
	s_waitcnt vmcnt(0)
	s_cmpk_gt_u32 s44, 0xff
	s_cbranch_scc1 .LBB0_1126
	s_barrier
